# lever 9 back-edge rotation: loop-carried SALU (counter updates + next-iteration address selects) of the five GEMM main loops moved in front of the closing barrier
# baseline (speedup 1.0000x reference)
; #define PG8_STAGE(bufoff, gbase, voff) do { _Pragma("unroll") for (int _i = 0; _i < 2; ++_i) \
;         __builtin_amdgcn_global_load_lds((const unsigned*)((const char*)(gbase) + (voff)[_i]), (LAS unsigned*)(lds + (bufoff) + ldsw + _i * 8192), 16, 0, 0); } while (0)
; #define PG8_LDA(dst, b, h) do { _Pragma("unroll") for (int m = 0; m < 4; ++m) _Pragma("unroll") for (int k = 0; k < 2; ++k) dst[m][k] = *(const LAS bf16x8*)(lds + PG8_SA(b, h) + aoff + m * 2048 + k * 1024); } while (0)
; #define PG8_LDB(dst, b, h) do { _Pragma("unroll") for (int n = 0; n < 2; ++n) _Pragma("unroll") for (int k = 0; k < 2; ++k) dst[n][k] = *(const LAS bf16x8*)(lds + PG8_SB(b, h) + boff + n * 2048 + k * 1024); } while (0)
; #define PG8_MMA(ai, bj, At, Bt) do { __builtin_amdgcn_s_setprio(1); _Pragma("unroll") for (int m = 0; m < 4; ++m) _Pragma("unroll") for (int n = 0; n < 2; ++n) _Pragma("unroll") for (int k = 0; k < 2; ++k) \
;         acc[ai][bj][m][n] = __builtin_amdgcn_mfma_f32_16x16x32_bf16(Bt[n][k], At[m][k], acc[ai][bj][m][n], 0, 0, 0); __builtin_amdgcn_s_setprio(0); } while (0)
; #define PG8_WAIT_V(n) asm volatile("s_waitcnt vmcnt(" #n ")" ::: "memory")
; #define PG8_WAIT_L(n) asm volatile("s_waitcnt lgkmcnt(" #n ")" ::: "memory")
; #define PG8_BAR __builtin_amdgcn_s_barrier()
; #define PG8_SCHED __builtin_amdgcn_sched_barrier(0)
; template <class Epi>
; __device__ __forceinline__ void gemm_phase(LAS unsigned char* lds, const Gemm g, const StaticOrder& S, const Epi& E) {
;     ...
;         for (int t = 0; t < nt; t += 2) {
;             const bool last = (t == nt - 2);
;             const char* a1 = cA + (size_t)(t + 1) * kstep;
;             const char* a2 = last ? nA : cA + (size_t)(t + 2) * kstep; const char* b2 = last ? nB : cB + (size_t)(t + 2) * kstep;
;             const char* a3 = a2 + kstep; const char* b3 = b2 + kstep;
;             PG8_LDB(B0, 0, 0); PG8_LDB(B1, 0, 1); PG8_SCHED; PG8_LDA(At, 0, 0); PG8_STAGE(PG8_SA(1, 1), a1 + hA, voffA);
;             PG8_WAIT_V(8); PG8_WAIT_L(0); PG8_BAR; PG8_MMA(0, 0, At, B0); PG8_MMA(0, 1, At, B1); PG8_BAR; PG8_SCHED;
;             PG8_LDA(At, 0, 1); PG8_STAGE(PG8_SB(0, 0), b2, voffB); PG8_STAGE(PG8_SB(0, 1), b2 + hB, voffB); PG8_STAGE(PG8_SA(0, 0), a2, voffA);
;             PG8_WAIT_V(8); PG8_WAIT_L(0); PG8_BAR; PG8_MMA(1, 0, At, B0); PG8_MMA(1, 1, At, B1); PG8_BAR; PG8_SCHED;
.LBB0_132:
	s_add_u32 s34, s8, 0xfffc0080
	s_addc_u32 s35, s9, -1
	s_add_i32 s42, 0, 0x10000
	s_cmp_eq_u32 s41, 12
	s_cselect_b32 s37, s7, s35
	s_cselect_b32 s36, s27, s34
	s_cselect_b32 s35, s25, s40
	s_cselect_b32 s34, s38, s39
	s_add_i32 s44, 0, 0x14000
.Lrot_132:
	v_add_u32_e32 v153, s42, v139
	ds_read_b128 v[166:169], v153
	ds_read_b128 v[170:173], v153 offset:1024
	ds_read_b128 v[174:177], v153 offset:2048
	ds_read_b128 v[182:185], v153 offset:3072
	v_add_u32_e32 v153, s44, v139
	ds_read_b128 v[186:189], v153
	ds_read_b128 v[190:193], v153 offset:1024
	ds_read_b128 v[194:197], v153 offset:2048
	ds_read_b128 v[198:201], v153 offset:3072
	v_lshl_add_u64 v[178:179], s[8:9], 0, v[162:163]
	s_add_i32 m0, s19, 0xc000
	ds_read_b128 v[202:205], v149
	ds_read_b128 v[206:209], v149 offset:1024
	ds_read_b128 v[210:213], v149 offset:2048
	ds_read_b128 v[214:217], v149 offset:3072
	ds_read_b128 v[218:221], v149 offset:4096
	ds_read_b128 v[232:235], v149 offset:5120
	ds_read_b128 v[236:239], v149 offset:6144
	ds_read_b128 v[240:243], v149 offset:7168
	global_load_lds_dwordx4 v[178:179], off
	v_lshl_add_u64 v[178:179], s[8:9], 0, v[164:165]
	s_add_i32 m0, s19, 0xe000
	s_nop 0
	global_load_lds_dwordx4 v[178:179], off
	s_waitcnt vmcnt(8)
	s_waitcnt lgkmcnt(0)
	s_barrier
	s_setprio 1
	s_waitcnt lgkmcnt(0)
	v_mfma_f32_16x16x32_bf16 v[126:129], v[166:169], v[202:205], v[126:129]
	v_mfma_f32_16x16x32_bf16 v[122:125], v[174:177], v[202:205], v[122:125]
	v_mfma_f32_16x16x32_bf16 v[110:113], v[166:169], v[210:213], v[110:113]
	v_mfma_f32_16x16x32_bf16 v[106:109], v[174:177], v[210:213], v[106:109]
	v_mfma_f32_16x16x32_bf16 v[94:97], v[166:169], v[218:221], v[94:97]
	v_mfma_f32_16x16x32_bf16 v[90:93], v[174:177], v[218:221], v[90:93]
	v_mfma_f32_16x16x32_bf16 v[78:81], v[166:169], v[236:239], v[78:81]
	v_mfma_f32_16x16x32_bf16 v[74:77], v[174:177], v[236:239], v[74:77]
	v_mfma_f32_16x16x32_bf16 v[126:129], v[170:173], v[206:209], v[126:129]
	v_mfma_f32_16x16x32_bf16 v[122:125], v[182:185], v[206:209], v[122:125]
	v_mfma_f32_16x16x32_bf16 v[110:113], v[170:173], v[214:217], v[110:113]
	v_mfma_f32_16x16x32_bf16 v[106:109], v[182:185], v[214:217], v[106:109]
	v_mfma_f32_16x16x32_bf16 v[94:97], v[170:173], v[232:235], v[94:97]
	v_mfma_f32_16x16x32_bf16 v[90:93], v[182:185], v[232:235], v[90:93]
	v_mfma_f32_16x16x32_bf16 v[78:81], v[170:173], v[240:243], v[78:81]
	v_mfma_f32_16x16x32_bf16 v[74:77], v[182:185], v[240:243], v[74:77]
	s_setprio 0
	s_setprio 1
	v_mfma_f32_16x16x32_bf16 v[118:121], v[186:189], v[202:205], v[118:121]
	v_mfma_f32_16x16x32_bf16 v[114:117], v[194:197], v[202:205], v[114:117]
	v_mfma_f32_16x16x32_bf16 v[102:105], v[186:189], v[210:213], v[102:105]
	v_mfma_f32_16x16x32_bf16 v[98:101], v[194:197], v[210:213], v[98:101]
	v_mfma_f32_16x16x32_bf16 v[86:89], v[186:189], v[218:221], v[86:89]
	v_mfma_f32_16x16x32_bf16 v[82:85], v[194:197], v[218:221], v[82:85]
	v_mfma_f32_16x16x32_bf16 v[70:73], v[186:189], v[236:239], v[70:73]
	v_mfma_f32_16x16x32_bf16 v[66:69], v[194:197], v[236:239], v[66:69]
	v_mfma_f32_16x16x32_bf16 v[118:121], v[190:193], v[206:209], v[118:121]
	v_mfma_f32_16x16x32_bf16 v[114:117], v[198:201], v[206:209], v[114:117]
	v_mfma_f32_16x16x32_bf16 v[102:105], v[190:193], v[214:217], v[102:105]
	v_mfma_f32_16x16x32_bf16 v[98:101], v[198:201], v[214:217], v[98:101]
	v_mfma_f32_16x16x32_bf16 v[86:89], v[190:193], v[232:235], v[86:89]
	v_mfma_f32_16x16x32_bf16 v[82:85], v[198:201], v[232:235], v[82:85]
	v_mfma_f32_16x16x32_bf16 v[70:73], v[190:193], v[240:243], v[70:73]
	v_mfma_f32_16x16x32_bf16 v[66:69], v[198:201], v[240:243], v[66:69]
	s_setprio 0
	s_barrier
	s_add_i32 s42, s42, s51
	v_lshl_add_u64 v[178:179], s[34:35], 0, v[132:133]
	s_mov_b32 m0, s42
	ds_read_b128 v[202:205], v149 offset:16384
	ds_read_b128 v[206:209], v149 offset:17408
	ds_read_b128 v[210:213], v149 offset:18432
	ds_read_b128 v[214:217], v149 offset:19456
	ds_read_b128 v[218:221], v149 offset:20480
	ds_read_b128 v[232:235], v149 offset:21504
	ds_read_b128 v[236:239], v149 offset:22528
	ds_read_b128 v[240:243], v149 offset:23552
	global_load_lds_dwordx4 v[178:179], off
	s_add_i32 m0, s42, 0x2000
	s_add_u32 s42, s34, 0x40000
	v_lshl_add_u64 v[244:245], s[34:35], 0, v[136:137]
	s_addc_u32 s43, s35, 0
	s_add_i32 s44, s44, s51
	global_load_lds_dwordx4 v[244:245], off
	v_lshl_add_u64 v[246:247], s[42:43], 0, v[132:133]
	s_mov_b32 m0, s44
	v_lshl_add_u64 v[248:249], s[36:37], 0, v[134:135]
	global_load_lds_dwordx4 v[246:247], off
	v_lshl_add_u64 v[246:247], s[42:43], 0, v[136:137]
	s_add_i32 m0, s44, 0x2000
	s_nop 0
	global_load_lds_dwordx4 v[246:247], off
	v_lshl_add_u64 v[246:247], s[36:37], 0, v[130:131]
	s_mov_b32 m0, s19
	s_nop 0
	global_load_lds_dwordx4 v[246:247], off
	s_mov_b32 m0, s56
	s_nop 0
	global_load_lds_dwordx4 v[248:249], off
	s_waitcnt vmcnt(8)
	s_waitcnt lgkmcnt(0)
	s_barrier
; #define PG8_STAGE(bufoff, gbase, voff) do { _Pragma("unroll") for (int _i = 0; _i < 2; ++_i) \
;         __builtin_amdgcn_global_load_lds((const unsigned*)((const char*)(gbase) + (voff)[_i]), (LAS unsigned*)(lds + (bufoff) + ldsw + _i * 8192), 16, 0, 0); } while (0)
; #define PG8_LDA(dst, b, h) do { _Pragma("unroll") for (int m = 0; m < 4; ++m) _Pragma("unroll") for (int k = 0; k < 2; ++k) dst[m][k] = *(const LAS bf16x8*)(lds + PG8_SA(b, h) + aoff + m * 2048 + k * 1024); } while (0)
; #define PG8_LDB(dst, b, h) do { _Pragma("unroll") for (int n = 0; n < 2; ++n) _Pragma("unroll") for (int k = 0; k < 2; ++k) dst[n][k] = *(const LAS bf16x8*)(lds + PG8_SB(b, h) + boff + n * 2048 + k * 1024); } while (0)
; #define PG8_MMA(ai, bj, At, Bt) do { __builtin_amdgcn_s_setprio(1); _Pragma("unroll") for (int m = 0; m < 4; ++m) _Pragma("unroll") for (int n = 0; n < 2; ++n) _Pragma("unroll") for (int k = 0; k < 2; ++k) \
;         acc[ai][bj][m][n] = __builtin_amdgcn_mfma_f32_16x16x32_bf16(Bt[n][k], At[m][k], acc[ai][bj][m][n], 0, 0, 0); __builtin_amdgcn_s_setprio(0); } while (0)
; #define PG8_WAIT_V(n) asm volatile("s_waitcnt vmcnt(" #n ")" ::: "memory")
; #define PG8_WAIT_L(n) asm volatile("s_waitcnt lgkmcnt(" #n ")" ::: "memory")
; #define PG8_BAR __builtin_amdgcn_s_barrier()
; #define PG8_SCHED __builtin_amdgcn_sched_barrier(0)
; template <class Epi>
; __device__ __forceinline__ void gemm_phase(LAS unsigned char* lds, const Gemm g, const StaticOrder& S, const Epi& E) {
;     ...
;             PG8_LDA(At, 0, 1); PG8_STAGE(PG8_SB(0, 0), b2, voffB); PG8_STAGE(PG8_SB(0, 1), b2 + hB, voffB); PG8_STAGE(PG8_SA(0, 0), a2, voffA);
;             PG8_WAIT_V(8); PG8_WAIT_L(0); PG8_BAR; PG8_MMA(1, 0, At, B0); PG8_MMA(1, 1, At, B1); PG8_BAR; PG8_SCHED;
;             PG8_LDB(B0, 1, 0); PG8_LDB(B1, 1, 1); PG8_SCHED; PG8_LDA(At, 1, 0); PG8_STAGE(PG8_SA(0, 1), a2 + hA, voffA);
;             PG8_WAIT_V(8); PG8_WAIT_L(0); PG8_BAR; PG8_MMA(0, 0, At, B0); PG8_MMA(0, 1, At, B1); PG8_BAR; PG8_SCHED;
;             PG8_LDA(At, 1, 1); PG8_STAGE(PG8_SB(1, 0), b3, voffB); PG8_STAGE(PG8_SB(1, 1), b3 + hB, voffB); PG8_STAGE(PG8_SA(1, 0), a3, voffA);
	s_setprio 1
	s_waitcnt lgkmcnt(0)
	v_mfma_f32_16x16x32_bf16 v[62:65], v[166:169], v[202:205], v[62:65]
	v_mfma_f32_16x16x32_bf16 v[58:61], v[174:177], v[202:205], v[58:61]
	v_mfma_f32_16x16x32_bf16 v[46:49], v[166:169], v[210:213], v[46:49]
	v_mfma_f32_16x16x32_bf16 v[42:45], v[174:177], v[210:213], v[42:45]
	v_mfma_f32_16x16x32_bf16 v[30:33], v[166:169], v[218:221], v[30:33]
	v_mfma_f32_16x16x32_bf16 v[26:29], v[174:177], v[218:221], v[26:29]
	v_mfma_f32_16x16x32_bf16 v[14:17], v[166:169], v[236:239], v[14:17]
	v_mfma_f32_16x16x32_bf16 v[10:13], v[174:177], v[236:239], v[10:13]
	v_mfma_f32_16x16x32_bf16 v[62:65], v[170:173], v[206:209], v[62:65]
	v_mfma_f32_16x16x32_bf16 v[58:61], v[182:185], v[206:209], v[58:61]
	v_mfma_f32_16x16x32_bf16 v[46:49], v[170:173], v[214:217], v[46:49]
	v_mfma_f32_16x16x32_bf16 v[42:45], v[182:185], v[214:217], v[42:45]
	v_mfma_f32_16x16x32_bf16 v[30:33], v[170:173], v[232:235], v[30:33]
	v_mfma_f32_16x16x32_bf16 v[26:29], v[182:185], v[232:235], v[26:29]
	v_mfma_f32_16x16x32_bf16 v[14:17], v[170:173], v[240:243], v[14:17]
	v_mfma_f32_16x16x32_bf16 v[10:13], v[182:185], v[240:243], v[10:13]
	s_setprio 0
	s_setprio 1
	v_mfma_f32_16x16x32_bf16 v[54:57], v[186:189], v[202:205], v[54:57]
	v_mfma_f32_16x16x32_bf16 v[50:53], v[194:197], v[202:205], v[50:53]
	v_mfma_f32_16x16x32_bf16 v[38:41], v[186:189], v[210:213], v[38:41]
	v_mfma_f32_16x16x32_bf16 v[34:37], v[194:197], v[210:213], v[34:37]
	v_mfma_f32_16x16x32_bf16 v[22:25], v[186:189], v[218:221], v[22:25]
	v_mfma_f32_16x16x32_bf16 v[18:21], v[194:197], v[218:221], v[18:21]
	v_mfma_f32_16x16x32_bf16 v[6:9], v[186:189], v[236:239], v[6:9]
	v_mfma_f32_16x16x32_bf16 v[2:5], v[194:197], v[236:239], v[2:5]
	v_mfma_f32_16x16x32_bf16 v[54:57], v[190:193], v[206:209], v[54:57]
	v_mfma_f32_16x16x32_bf16 v[50:53], v[198:201], v[206:209], v[50:53]
	v_mfma_f32_16x16x32_bf16 v[38:41], v[190:193], v[214:217], v[38:41]
	v_mfma_f32_16x16x32_bf16 v[34:37], v[198:201], v[214:217], v[34:37]
	v_mfma_f32_16x16x32_bf16 v[22:25], v[190:193], v[232:235], v[22:25]
	v_mfma_f32_16x16x32_bf16 v[18:21], v[198:201], v[232:235], v[18:21]
	v_mfma_f32_16x16x32_bf16 v[6:9], v[190:193], v[240:243], v[6:9]
	v_mfma_f32_16x16x32_bf16 v[2:5], v[198:201], v[240:243], v[2:5]
	s_setprio 0
	s_barrier
	s_add_i32 s42, 0, 0x18000
	v_add_u32_e32 v153, s42, v139
	s_add_i32 s43, 0, 0x1c000
	ds_read_b128 v[166:169], v153
	ds_read_b128 v[170:173], v153 offset:1024
	ds_read_b128 v[174:177], v153 offset:2048
	ds_read_b128 v[182:185], v153 offset:3072
	v_add_u32_e32 v153, s43, v139
	ds_read_b128 v[186:189], v153
	ds_read_b128 v[190:193], v153 offset:1024
	ds_read_b128 v[194:197], v153 offset:2048
	ds_read_b128 v[198:201], v153 offset:3072
	s_add_u32 s36, s36, 0x40000
	s_addc_u32 s37, s37, 0
	s_mov_b32 m0, s57
	v_lshl_add_u64 v[250:251], s[36:37], 0, v[130:131]
	ds_read_b128 v[202:205], v149 offset:32768
	ds_read_b128 v[206:209], v149 offset:33792
	ds_read_b128 v[210:213], v149 offset:34816
	ds_read_b128 v[214:217], v149 offset:35840
	ds_read_b128 v[218:221], v149 offset:36864
	ds_read_b128 v[232:235], v149 offset:37888
	ds_read_b128 v[236:239], v149 offset:38912
	ds_read_b128 v[240:243], v149 offset:39936
	global_load_lds_dwordx4 v[250:251], off
	v_lshl_add_u64 v[250:251], s[36:37], 0, v[134:135]
	s_mov_b32 m0, s58
	s_nop 0
	global_load_lds_dwordx4 v[250:251], off
	s_waitcnt vmcnt(8)
	s_waitcnt lgkmcnt(0)
	s_barrier
	s_setprio 1
	s_waitcnt lgkmcnt(0)
	v_mfma_f32_16x16x32_bf16 v[126:129], v[166:169], v[202:205], v[126:129]
	v_mfma_f32_16x16x32_bf16 v[122:125], v[174:177], v[202:205], v[122:125]
	v_mfma_f32_16x16x32_bf16 v[110:113], v[166:169], v[210:213], v[110:113]
	v_mfma_f32_16x16x32_bf16 v[106:109], v[174:177], v[210:213], v[106:109]
	v_mfma_f32_16x16x32_bf16 v[94:97], v[166:169], v[218:221], v[94:97]
	v_mfma_f32_16x16x32_bf16 v[90:93], v[174:177], v[218:221], v[90:93]
	v_mfma_f32_16x16x32_bf16 v[78:81], v[166:169], v[236:239], v[78:81]
	v_mfma_f32_16x16x32_bf16 v[74:77], v[174:177], v[236:239], v[74:77]
	v_mfma_f32_16x16x32_bf16 v[126:129], v[170:173], v[206:209], v[126:129]
	v_mfma_f32_16x16x32_bf16 v[122:125], v[182:185], v[206:209], v[122:125]
	v_mfma_f32_16x16x32_bf16 v[110:113], v[170:173], v[214:217], v[110:113]
	v_mfma_f32_16x16x32_bf16 v[106:109], v[182:185], v[214:217], v[106:109]
	v_mfma_f32_16x16x32_bf16 v[94:97], v[170:173], v[232:235], v[94:97]
	v_mfma_f32_16x16x32_bf16 v[90:93], v[182:185], v[232:235], v[90:93]
	v_mfma_f32_16x16x32_bf16 v[78:81], v[170:173], v[240:243], v[78:81]
	v_mfma_f32_16x16x32_bf16 v[74:77], v[182:185], v[240:243], v[74:77]
	s_setprio 0
	s_setprio 1
	v_mfma_f32_16x16x32_bf16 v[118:121], v[186:189], v[202:205], v[118:121]
	v_mfma_f32_16x16x32_bf16 v[114:117], v[194:197], v[202:205], v[114:117]
	v_mfma_f32_16x16x32_bf16 v[102:105], v[186:189], v[210:213], v[102:105]
	v_mfma_f32_16x16x32_bf16 v[98:101], v[194:197], v[210:213], v[98:101]
	v_mfma_f32_16x16x32_bf16 v[86:89], v[186:189], v[218:221], v[86:89]
	v_mfma_f32_16x16x32_bf16 v[82:85], v[194:197], v[218:221], v[82:85]
	v_mfma_f32_16x16x32_bf16 v[70:73], v[186:189], v[236:239], v[70:73]
	v_mfma_f32_16x16x32_bf16 v[66:69], v[194:197], v[236:239], v[66:69]
	v_mfma_f32_16x16x32_bf16 v[118:121], v[190:193], v[206:209], v[118:121]
	v_mfma_f32_16x16x32_bf16 v[114:117], v[198:201], v[206:209], v[114:117]
	v_mfma_f32_16x16x32_bf16 v[102:105], v[190:193], v[214:217], v[102:105]
	v_mfma_f32_16x16x32_bf16 v[98:101], v[198:201], v[214:217], v[98:101]
	v_mfma_f32_16x16x32_bf16 v[86:89], v[190:193], v[232:235], v[86:89]
	v_mfma_f32_16x16x32_bf16 v[82:85], v[198:201], v[232:235], v[82:85]
	v_mfma_f32_16x16x32_bf16 v[70:73], v[190:193], v[240:243], v[70:73]
	v_mfma_f32_16x16x32_bf16 v[66:69], v[198:201], v[240:243], v[66:69]
	s_setprio 0
	s_barrier
; #define PG8_STAGE(bufoff, gbase, voff) do { _Pragma("unroll") for (int _i = 0; _i < 2; ++_i) \
;         __builtin_amdgcn_global_load_lds((const unsigned*)((const char*)(gbase) + (voff)[_i]), (LAS unsigned*)(lds + (bufoff) + ldsw + _i * 8192), 16, 0, 0); } while (0)
; #define PG8_LDA(dst, b, h) do { _Pragma("unroll") for (int m = 0; m < 4; ++m) _Pragma("unroll") for (int k = 0; k < 2; ++k) dst[m][k] = *(const LAS bf16x8*)(lds + PG8_SA(b, h) + aoff + m * 2048 + k * 1024); } while (0)
; #define PG8_LDB(dst, b, h) do { _Pragma("unroll") for (int n = 0; n < 2; ++n) _Pragma("unroll") for (int k = 0; k < 2; ++k) dst[n][k] = *(const LAS bf16x8*)(lds + PG8_SB(b, h) + boff + n * 2048 + k * 1024); } while (0)
; #define PG8_MMA(ai, bj, At, Bt) do { __builtin_amdgcn_s_setprio(1); _Pragma("unroll") for (int m = 0; m < 4; ++m) _Pragma("unroll") for (int n = 0; n < 2; ++n) _Pragma("unroll") for (int k = 0; k < 2; ++k) \
;         acc[ai][bj][m][n] = __builtin_amdgcn_mfma_f32_16x16x32_bf16(Bt[n][k], At[m][k], acc[ai][bj][m][n], 0, 0, 0); __builtin_amdgcn_s_setprio(0); } while (0)
; #define PG8_WAIT_V(n) asm volatile("s_waitcnt vmcnt(" #n ")" ::: "memory")
; #define PG8_WAIT_L(n) asm volatile("s_waitcnt lgkmcnt(" #n ")" ::: "memory")
; #define PG8_BAR __builtin_amdgcn_s_barrier()
; #define PG8_SCHED __builtin_amdgcn_sched_barrier(0)
; template <class Epi>
; __device__ __forceinline__ void gemm_phase(LAS unsigned char* lds, const Gemm g, const StaticOrder& S, const Epi& E) {
;     ...
;             PG8_LDB(B0, 1, 0); PG8_LDB(B1, 1, 1); PG8_SCHED; PG8_LDA(At, 1, 0); PG8_STAGE(PG8_SA(0, 1), a2 + hA, voffA);
;             PG8_WAIT_V(8); PG8_WAIT_L(0); PG8_BAR; PG8_MMA(0, 0, At, B0); PG8_MMA(0, 1, At, B1); PG8_BAR; PG8_SCHED;
;             PG8_LDA(At, 1, 1); PG8_STAGE(PG8_SB(1, 0), b3, voffB); PG8_STAGE(PG8_SB(1, 1), b3 + hB, voffB); PG8_STAGE(PG8_SA(1, 0), a3, voffA);
;             PG8_WAIT_V(8); PG8_WAIT_L(0); PG8_BAR; PG8_MMA(1, 0, At, B0); PG8_MMA(1, 1, At, B1); PG8_BAR; PG8_SCHED;
;         }
	s_add_i32 s36, s42, s51
	v_lshl_add_u64 v[178:179], v[178:179], 0, s[88:89]
	s_mov_b32 m0, s36
	ds_read_b128 v[202:205], v149 offset:49152
	ds_read_b128 v[206:209], v149 offset:50176
	ds_read_b128 v[210:213], v149 offset:51200
	ds_read_b128 v[214:217], v149 offset:52224
	ds_read_b128 v[218:221], v149 offset:53248
	ds_read_b128 v[232:235], v149 offset:54272
	ds_read_b128 v[236:239], v149 offset:55296
	ds_read_b128 v[240:243], v149 offset:56320
	global_load_lds_dwordx4 v[178:179], off
	s_add_i32 m0, s36, 0x2000
	s_add_u32 s34, s34, 0x40080
	v_lshl_add_u64 v[178:179], v[244:245], 0, s[88:89]
	s_addc_u32 s35, s35, 0
	s_add_i32 s36, s43, s51
	global_load_lds_dwordx4 v[178:179], off
	v_lshl_add_u64 v[178:179], s[34:35], 0, v[132:133]
	s_mov_b32 m0, s36
	s_nop 0
	global_load_lds_dwordx4 v[178:179], off
	v_lshl_add_u64 v[178:179], s[34:35], 0, v[136:137]
	s_add_i32 m0, s36, 0x2000
	s_nop 0
	global_load_lds_dwordx4 v[178:179], off
	v_lshl_add_u64 v[178:179], v[246:247], 0, s[88:89]
	s_mov_b32 m0, s60
	s_nop 0
	global_load_lds_dwordx4 v[178:179], off
	v_lshl_add_u64 v[178:179], v[248:249], 0, s[88:89]
	s_mov_b32 m0, s61
	s_nop 0
	global_load_lds_dwordx4 v[178:179], off
	s_waitcnt vmcnt(8)
	s_waitcnt lgkmcnt(0)
	s_barrier
	s_setprio 1
	s_waitcnt lgkmcnt(0)
	v_mfma_f32_16x16x32_bf16 v[62:65], v[166:169], v[202:205], v[62:65]
	v_mfma_f32_16x16x32_bf16 v[58:61], v[174:177], v[202:205], v[58:61]
	v_mfma_f32_16x16x32_bf16 v[46:49], v[166:169], v[210:213], v[46:49]
	v_mfma_f32_16x16x32_bf16 v[42:45], v[174:177], v[210:213], v[42:45]
	v_mfma_f32_16x16x32_bf16 v[30:33], v[166:169], v[218:221], v[30:33]
	v_mfma_f32_16x16x32_bf16 v[26:29], v[174:177], v[218:221], v[26:29]
	v_mfma_f32_16x16x32_bf16 v[14:17], v[166:169], v[236:239], v[14:17]
	v_mfma_f32_16x16x32_bf16 v[10:13], v[174:177], v[236:239], v[10:13]
	v_mfma_f32_16x16x32_bf16 v[62:65], v[170:173], v[206:209], v[62:65]
	v_mfma_f32_16x16x32_bf16 v[58:61], v[182:185], v[206:209], v[58:61]
	v_mfma_f32_16x16x32_bf16 v[46:49], v[170:173], v[214:217], v[46:49]
	v_mfma_f32_16x16x32_bf16 v[42:45], v[182:185], v[214:217], v[42:45]
	v_mfma_f32_16x16x32_bf16 v[30:33], v[170:173], v[232:235], v[30:33]
	v_mfma_f32_16x16x32_bf16 v[26:29], v[182:185], v[232:235], v[26:29]
	v_mfma_f32_16x16x32_bf16 v[14:17], v[170:173], v[240:243], v[14:17]
	v_mfma_f32_16x16x32_bf16 v[10:13], v[182:185], v[240:243], v[10:13]
	s_setprio 0
	s_setprio 1
	v_mfma_f32_16x16x32_bf16 v[54:57], v[186:189], v[202:205], v[54:57]
	v_mfma_f32_16x16x32_bf16 v[50:53], v[194:197], v[202:205], v[50:53]
	v_mfma_f32_16x16x32_bf16 v[38:41], v[186:189], v[210:213], v[38:41]
	v_mfma_f32_16x16x32_bf16 v[34:37], v[194:197], v[210:213], v[34:37]
	v_mfma_f32_16x16x32_bf16 v[22:25], v[186:189], v[218:221], v[22:25]
	v_mfma_f32_16x16x32_bf16 v[18:21], v[194:197], v[218:221], v[18:21]
	v_mfma_f32_16x16x32_bf16 v[6:9], v[186:189], v[236:239], v[6:9]
	v_mfma_f32_16x16x32_bf16 v[2:5], v[194:197], v[236:239], v[2:5]
	v_mfma_f32_16x16x32_bf16 v[54:57], v[190:193], v[206:209], v[54:57]
	v_mfma_f32_16x16x32_bf16 v[50:53], v[198:201], v[206:209], v[50:53]
	v_mfma_f32_16x16x32_bf16 v[38:41], v[190:193], v[214:217], v[38:41]
	v_mfma_f32_16x16x32_bf16 v[34:37], v[198:201], v[214:217], v[34:37]
	v_mfma_f32_16x16x32_bf16 v[22:25], v[190:193], v[232:235], v[22:25]
	v_mfma_f32_16x16x32_bf16 v[18:21], v[198:201], v[232:235], v[18:21]
	v_mfma_f32_16x16x32_bf16 v[6:9], v[190:193], v[240:243], v[6:9]
	v_mfma_f32_16x16x32_bf16 v[2:5], v[198:201], v[240:243], v[2:5]
	s_setprio 0
	s_add_i32 s41, s41, 2
	s_add_u32 s8, s8, 0x100
	s_addc_u32 s9, s9, 0
	s_add_u32 s39, s39, 0x100
	s_addc_u32 s40, s40, 0
	s_add_u32 s34, s8, 0xfffc0080
	s_addc_u32 s35, s9, -1
	s_add_i32 s42, 0, 0x10000
	s_cmp_eq_u32 s41, 12
	s_cselect_b32 s37, s7, s35
	s_cselect_b32 s36, s27, s34
	s_cselect_b32 s35, s25, s40
	s_cselect_b32 s34, s38, s39
	s_add_i32 s44, 0, 0x14000
	s_cmp_gt_u32 s41, 13
	s_barrier
	s_cbranch_scc0 .Lrot_132
	s_and_b64 vcc, exec, s[16:17]
	s_cbranch_vccz .LBB0_135
	s_barrier

; #define PG8_STAGE(bufoff, gbase, voff) do { _Pragma("unroll") for (int _i = 0; _i < 2; ++_i) \
;         __builtin_amdgcn_global_load_lds((const unsigned*)((const char*)(gbase) + (voff)[_i]), (LAS unsigned*)(lds + (bufoff) + ldsw + _i * 8192), 16, 0, 0); } while (0)
; #define PG8_LDA(dst, b, h) do { _Pragma("unroll") for (int m = 0; m < 4; ++m) _Pragma("unroll") for (int k = 0; k < 2; ++k) dst[m][k] = *(const LAS bf16x8*)(lds + PG8_SA(b, h) + aoff + m * 2048 + k * 1024); } while (0)
; #define PG8_LDB(dst, b, h) do { _Pragma("unroll") for (int n = 0; n < 2; ++n) _Pragma("unroll") for (int k = 0; k < 2; ++k) dst[n][k] = *(const LAS bf16x8*)(lds + PG8_SB(b, h) + boff + n * 2048 + k * 1024); } while (0)
; #define PG8_MMA(ai, bj, At, Bt) do { __builtin_amdgcn_s_setprio(1); _Pragma("unroll") for (int m = 0; m < 4; ++m) _Pragma("unroll") for (int n = 0; n < 2; ++n) _Pragma("unroll") for (int k = 0; k < 2; ++k) \
;         acc[ai][bj][m][n] = __builtin_amdgcn_mfma_f32_16x16x32_bf16(Bt[n][k], At[m][k], acc[ai][bj][m][n], 0, 0, 0); __builtin_amdgcn_s_setprio(0); } while (0)
; #define PG8_WAIT_V(n) asm volatile("s_waitcnt vmcnt(" #n ")" ::: "memory")
; #define PG8_WAIT_L(n) asm volatile("s_waitcnt lgkmcnt(" #n ")" ::: "memory")
; #define PG8_BAR __builtin_amdgcn_s_barrier()
; #define PG8_SCHED __builtin_amdgcn_sched_barrier(0)
; template <class Epi>
; __device__ __forceinline__ void gemm_phase(LAS unsigned char* lds, const Gemm g, const StaticOrder& S, const Epi& E) {
;     ...
;         for (int t = 0; t < nt; t += 2) {
;             const bool last = (t == nt - 2);
;             const char* a1 = cA + (size_t)(t + 1) * kstep;
;             const char* a2 = last ? nA : cA + (size_t)(t + 2) * kstep; const char* b2 = last ? nB : cB + (size_t)(t + 2) * kstep;
;             const char* a3 = a2 + kstep; const char* b3 = b2 + kstep;
;             PG8_LDB(B0, 0, 0); PG8_LDB(B1, 0, 1); PG8_SCHED; PG8_LDA(At, 0, 0); PG8_STAGE(PG8_SA(1, 1), a1 + hA, voffA);
;             PG8_WAIT_V(8); PG8_WAIT_L(0); PG8_BAR; PG8_MMA(0, 0, At, B0); PG8_MMA(0, 1, At, B1); PG8_BAR; PG8_SCHED;
;             PG8_LDA(At, 0, 1); PG8_STAGE(PG8_SB(0, 0), b2, voffB); PG8_STAGE(PG8_SB(0, 1), b2 + hB, voffB); PG8_STAGE(PG8_SA(0, 0), a2, voffA);
;             PG8_WAIT_V(8); PG8_WAIT_L(0); PG8_BAR; PG8_MMA(1, 0, At, B0); PG8_MMA(1, 1, At, B1); PG8_BAR; PG8_SCHED;
.LBB0_518:
	s_add_u32 s30, s28, 0xfffc0080
	s_addc_u32 s31, s29, -1
	s_add_i32 s71, 0, 0x10000
	s_cmp_eq_u32 s70, 28
	s_cselect_b32 s35, s21, s31
	s_cselect_b32 s34, s27, s30
	s_cselect_b32 s31, s19, s67
	s_cselect_b32 s30, s65, s66
	s_add_i32 s73, 0, 0x14000
.Lrot_518:
	v_add_u32_e32 v154, s71, v156
	ds_read_b128 v[98:101], v154
	ds_read_b128 v[102:105], v154 offset:1024
	ds_read_b128 v[158:161], v154 offset:2048
	ds_read_b128 v[162:165], v154 offset:3072
	v_add_u32_e32 v154, s73, v156
	ds_read_b128 v[166:169], v154
	ds_read_b128 v[170:173], v154 offset:1024
	ds_read_b128 v[174:177], v154 offset:2048
	ds_read_b128 v[182:185], v154 offset:3072
	v_lshl_add_u64 v[154:155], s[28:29], 0, v[150:151]
	s_add_i32 m0, s54, 0xc000
	ds_read_b128 v[186:189], v157
	ds_read_b128 v[190:193], v157 offset:1024
	ds_read_b128 v[194:197], v157 offset:2048
	ds_read_b128 v[198:201], v157 offset:3072
	ds_read_b128 v[202:205], v157 offset:4096
	ds_read_b128 v[206:209], v157 offset:5120
	ds_read_b128 v[210:213], v157 offset:6144
	ds_read_b128 v[214:217], v157 offset:7168
	global_load_lds_dwordx4 v[154:155], off
	v_lshl_add_u64 v[154:155], s[28:29], 0, v[152:153]
	s_add_i32 m0, s54, 0xe000
	s_nop 0
	global_load_lds_dwordx4 v[154:155], off
	s_waitcnt vmcnt(8)
	s_waitcnt lgkmcnt(0)
	s_barrier
	s_setprio 1
	s_waitcnt lgkmcnt(0)
	v_mfma_f32_16x16x32_bf16 v[134:137], v[98:101], v[186:189], v[134:137]
	v_mfma_f32_16x16x32_bf16 v[130:133], v[158:161], v[186:189], v[130:133]
	v_mfma_f32_16x16x32_bf16 v[126:129], v[98:101], v[194:197], v[126:129]
	v_mfma_f32_16x16x32_bf16 v[122:125], v[158:161], v[194:197], v[122:125]
	v_mfma_f32_16x16x32_bf16 v[118:121], v[98:101], v[202:205], v[118:121]
	v_mfma_f32_16x16x32_bf16 v[114:117], v[158:161], v[202:205], v[114:117]
	v_mfma_f32_16x16x32_bf16 v[110:113], v[98:101], v[210:213], v[110:113]
	v_mfma_f32_16x16x32_bf16 v[106:109], v[158:161], v[210:213], v[106:109]
	v_mfma_f32_16x16x32_bf16 v[134:137], v[102:105], v[190:193], v[134:137]
	v_mfma_f32_16x16x32_bf16 v[130:133], v[162:165], v[190:193], v[130:133]
	v_mfma_f32_16x16x32_bf16 v[126:129], v[102:105], v[198:201], v[126:129]
	v_mfma_f32_16x16x32_bf16 v[122:125], v[162:165], v[198:201], v[122:125]
	v_mfma_f32_16x16x32_bf16 v[118:121], v[102:105], v[206:209], v[118:121]
	v_mfma_f32_16x16x32_bf16 v[114:117], v[162:165], v[206:209], v[114:117]
	v_mfma_f32_16x16x32_bf16 v[110:113], v[102:105], v[214:217], v[110:113]
	v_mfma_f32_16x16x32_bf16 v[106:109], v[162:165], v[214:217], v[106:109]
	s_setprio 0
	s_setprio 1
	v_mfma_f32_16x16x32_bf16 v[62:65], v[166:169], v[186:189], v[62:65]
	v_mfma_f32_16x16x32_bf16 v[58:61], v[174:177], v[186:189], v[58:61]
	v_mfma_f32_16x16x32_bf16 v[54:57], v[166:169], v[194:197], v[54:57]
	v_mfma_f32_16x16x32_bf16 v[50:53], v[174:177], v[194:197], v[50:53]
	v_mfma_f32_16x16x32_bf16 v[46:49], v[166:169], v[202:205], v[46:49]
	v_mfma_f32_16x16x32_bf16 v[42:45], v[174:177], v[202:205], v[42:45]
	v_mfma_f32_16x16x32_bf16 v[38:41], v[166:169], v[210:213], v[38:41]
	v_mfma_f32_16x16x32_bf16 v[34:37], v[174:177], v[210:213], v[34:37]
	v_mfma_f32_16x16x32_bf16 v[62:65], v[170:173], v[190:193], v[62:65]
	v_mfma_f32_16x16x32_bf16 v[58:61], v[182:185], v[190:193], v[58:61]
	v_mfma_f32_16x16x32_bf16 v[54:57], v[170:173], v[198:201], v[54:57]
	v_mfma_f32_16x16x32_bf16 v[50:53], v[182:185], v[198:201], v[50:53]
	v_mfma_f32_16x16x32_bf16 v[46:49], v[170:173], v[206:209], v[46:49]
	v_mfma_f32_16x16x32_bf16 v[42:45], v[182:185], v[206:209], v[42:45]
	v_mfma_f32_16x16x32_bf16 v[38:41], v[170:173], v[214:217], v[38:41]
	v_mfma_f32_16x16x32_bf16 v[34:37], v[182:185], v[214:217], v[34:37]
	s_setprio 0
	s_barrier
	s_add_i32 s71, s71, s53
	v_lshl_add_u64 v[154:155], s[30:31], 0, v[140:141]
	s_mov_b32 m0, s71
	ds_read_b128 v[186:189], v157 offset:16384
	ds_read_b128 v[190:193], v157 offset:17408
	ds_read_b128 v[194:197], v157 offset:18432
	ds_read_b128 v[198:201], v157 offset:19456
	ds_read_b128 v[202:205], v157 offset:20480
	ds_read_b128 v[206:209], v157 offset:21504
	ds_read_b128 v[210:213], v157 offset:22528
	ds_read_b128 v[214:217], v157 offset:23552
	global_load_lds_dwordx4 v[154:155], off
	s_add_i32 m0, s71, 0x2000
	s_add_u32 s74, s30, 0x80000
	v_lshl_add_u64 v[178:179], s[30:31], 0, v[144:145]
	s_addc_u32 s75, s31, 0
	s_add_i32 s71, s73, s53
	global_load_lds_dwordx4 v[178:179], off
	v_lshl_add_u64 v[218:219], s[74:75], 0, v[140:141]
	s_mov_b32 m0, s71
	v_lshl_add_u64 v[220:221], s[34:35], 0, v[142:143]
	global_load_lds_dwordx4 v[218:219], off
	v_lshl_add_u64 v[218:219], s[74:75], 0, v[144:145]
	s_add_i32 m0, s71, 0x2000
	s_nop 0
	global_load_lds_dwordx4 v[218:219], off
	v_lshl_add_u64 v[218:219], s[34:35], 0, v[138:139]
	s_mov_b32 m0, s54
	s_nop 0
	global_load_lds_dwordx4 v[218:219], off
	s_mov_b32 m0, s55
	s_nop 0
	global_load_lds_dwordx4 v[220:221], off
	s_waitcnt vmcnt(8)
	s_waitcnt lgkmcnt(0)
	s_barrier
; #define PG8_STAGE(bufoff, gbase, voff) do { _Pragma("unroll") for (int _i = 0; _i < 2; ++_i) \
;         __builtin_amdgcn_global_load_lds((const unsigned*)((const char*)(gbase) + (voff)[_i]), (LAS unsigned*)(lds + (bufoff) + ldsw + _i * 8192), 16, 0, 0); } while (0)
; #define PG8_LDA(dst, b, h) do { _Pragma("unroll") for (int m = 0; m < 4; ++m) _Pragma("unroll") for (int k = 0; k < 2; ++k) dst[m][k] = *(const LAS bf16x8*)(lds + PG8_SA(b, h) + aoff + m * 2048 + k * 1024); } while (0)
; #define PG8_LDB(dst, b, h) do { _Pragma("unroll") for (int n = 0; n < 2; ++n) _Pragma("unroll") for (int k = 0; k < 2; ++k) dst[n][k] = *(const LAS bf16x8*)(lds + PG8_SB(b, h) + boff + n * 2048 + k * 1024); } while (0)
; #define PG8_MMA(ai, bj, At, Bt) do { __builtin_amdgcn_s_setprio(1); _Pragma("unroll") for (int m = 0; m < 4; ++m) _Pragma("unroll") for (int n = 0; n < 2; ++n) _Pragma("unroll") for (int k = 0; k < 2; ++k) \
;         acc[ai][bj][m][n] = __builtin_amdgcn_mfma_f32_16x16x32_bf16(Bt[n][k], At[m][k], acc[ai][bj][m][n], 0, 0, 0); __builtin_amdgcn_s_setprio(0); } while (0)
; #define PG8_WAIT_V(n) asm volatile("s_waitcnt vmcnt(" #n ")" ::: "memory")
; #define PG8_WAIT_L(n) asm volatile("s_waitcnt lgkmcnt(" #n ")" ::: "memory")
; #define PG8_BAR __builtin_amdgcn_s_barrier()
; #define PG8_SCHED __builtin_amdgcn_sched_barrier(0)
; template <class Epi>
; __device__ __forceinline__ void gemm_phase(LAS unsigned char* lds, const Gemm g, const StaticOrder& S, const Epi& E) {
;     ...
;             PG8_LDA(At, 0, 1); PG8_STAGE(PG8_SB(0, 0), b2, voffB); PG8_STAGE(PG8_SB(0, 1), b2 + hB, voffB); PG8_STAGE(PG8_SA(0, 0), a2, voffA);
;             PG8_WAIT_V(8); PG8_WAIT_L(0); PG8_BAR; PG8_MMA(1, 0, At, B0); PG8_MMA(1, 1, At, B1); PG8_BAR; PG8_SCHED;
;             PG8_LDB(B0, 1, 0); PG8_LDB(B1, 1, 1); PG8_SCHED; PG8_LDA(At, 1, 0); PG8_STAGE(PG8_SA(0, 1), a2 + hA, voffA);
;             PG8_WAIT_V(8); PG8_WAIT_L(0); PG8_BAR; PG8_MMA(0, 0, At, B0); PG8_MMA(0, 1, At, B1); PG8_BAR; PG8_SCHED;
;             PG8_LDA(At, 1, 1); PG8_STAGE(PG8_SB(1, 0), b3, voffB); PG8_STAGE(PG8_SB(1, 1), b3 + hB, voffB); PG8_STAGE(PG8_SA(1, 0), a3, voffA);
	s_setprio 1
	s_waitcnt lgkmcnt(0)
	v_mfma_f32_16x16x32_bf16 v[94:97], v[98:101], v[186:189], v[94:97]
	v_mfma_f32_16x16x32_bf16 v[90:93], v[158:161], v[186:189], v[90:93]
	v_mfma_f32_16x16x32_bf16 v[86:89], v[98:101], v[194:197], v[86:89]
	v_mfma_f32_16x16x32_bf16 v[82:85], v[158:161], v[194:197], v[82:85]
	v_mfma_f32_16x16x32_bf16 v[78:81], v[98:101], v[202:205], v[78:81]
	v_mfma_f32_16x16x32_bf16 v[74:77], v[158:161], v[202:205], v[74:77]
	v_mfma_f32_16x16x32_bf16 v[70:73], v[98:101], v[210:213], v[70:73]
	v_mfma_f32_16x16x32_bf16 v[66:69], v[158:161], v[210:213], v[66:69]
	v_mfma_f32_16x16x32_bf16 v[94:97], v[102:105], v[190:193], v[94:97]
	v_mfma_f32_16x16x32_bf16 v[90:93], v[162:165], v[190:193], v[90:93]
	v_mfma_f32_16x16x32_bf16 v[86:89], v[102:105], v[198:201], v[86:89]
	v_mfma_f32_16x16x32_bf16 v[82:85], v[162:165], v[198:201], v[82:85]
	v_mfma_f32_16x16x32_bf16 v[78:81], v[102:105], v[206:209], v[78:81]
	v_mfma_f32_16x16x32_bf16 v[74:77], v[162:165], v[206:209], v[74:77]
	v_mfma_f32_16x16x32_bf16 v[70:73], v[102:105], v[214:217], v[70:73]
	v_mfma_f32_16x16x32_bf16 v[66:69], v[162:165], v[214:217], v[66:69]
	s_setprio 0
	s_setprio 1
	v_mfma_f32_16x16x32_bf16 v[30:33], v[166:169], v[186:189], v[30:33]
	v_mfma_f32_16x16x32_bf16 v[26:29], v[174:177], v[186:189], v[26:29]
	v_mfma_f32_16x16x32_bf16 v[22:25], v[166:169], v[194:197], v[22:25]
	v_mfma_f32_16x16x32_bf16 v[18:21], v[174:177], v[194:197], v[18:21]
	v_mfma_f32_16x16x32_bf16 v[14:17], v[166:169], v[202:205], v[14:17]
	v_mfma_f32_16x16x32_bf16 v[10:13], v[174:177], v[202:205], v[10:13]
	v_mfma_f32_16x16x32_bf16 v[6:9], v[166:169], v[210:213], v[6:9]
	v_mfma_f32_16x16x32_bf16 v[2:5], v[174:177], v[210:213], v[2:5]
	v_mfma_f32_16x16x32_bf16 v[30:33], v[170:173], v[190:193], v[30:33]
	v_mfma_f32_16x16x32_bf16 v[26:29], v[182:185], v[190:193], v[26:29]
	v_mfma_f32_16x16x32_bf16 v[22:25], v[170:173], v[198:201], v[22:25]
	v_mfma_f32_16x16x32_bf16 v[18:21], v[182:185], v[198:201], v[18:21]
	v_mfma_f32_16x16x32_bf16 v[14:17], v[170:173], v[206:209], v[14:17]
	v_mfma_f32_16x16x32_bf16 v[10:13], v[182:185], v[206:209], v[10:13]
	v_mfma_f32_16x16x32_bf16 v[6:9], v[170:173], v[214:217], v[6:9]
	v_mfma_f32_16x16x32_bf16 v[2:5], v[182:185], v[214:217], v[2:5]
	s_setprio 0
	s_barrier
	s_add_i32 s71, 0, 0x18000
	s_add_i32 s73, 0, 0x1c000
	v_add_u32_e32 v162, s71, v156
	v_add_u32_e32 v180, s73, v156
	ds_read_b128 v[98:101], v162
	ds_read_b128 v[102:105], v162 offset:1024
	ds_read_b128 v[158:161], v162 offset:2048
	ds_read_b128 v[162:165], v162 offset:3072
	ds_read_b128 v[166:169], v180
	ds_read_b128 v[170:173], v180 offset:1024
	ds_read_b128 v[174:177], v180 offset:2048
	ds_read_b128 v[182:185], v180 offset:3072
	s_add_u32 s34, s34, 0x40000
	s_addc_u32 s35, s35, 0
	s_mov_b32 m0, s56
	v_lshl_add_u64 v[232:233], s[34:35], 0, v[138:139]
	ds_read_b128 v[186:189], v157 offset:32768
	ds_read_b128 v[190:193], v157 offset:33792
	ds_read_b128 v[194:197], v157 offset:34816
	ds_read_b128 v[198:201], v157 offset:35840
	ds_read_b128 v[202:205], v157 offset:36864
	ds_read_b128 v[206:209], v157 offset:37888
	ds_read_b128 v[210:213], v157 offset:38912
	ds_read_b128 v[214:217], v157 offset:39936
	global_load_lds_dwordx4 v[232:233], off
	v_lshl_add_u64 v[232:233], s[34:35], 0, v[142:143]
	s_mov_b32 m0, s57
	s_nop 0
	global_load_lds_dwordx4 v[232:233], off
	s_waitcnt vmcnt(8)
	s_waitcnt lgkmcnt(0)
	s_barrier
	s_setprio 1
	s_waitcnt lgkmcnt(0)
	v_mfma_f32_16x16x32_bf16 v[134:137], v[98:101], v[186:189], v[134:137]
	v_mfma_f32_16x16x32_bf16 v[130:133], v[158:161], v[186:189], v[130:133]
	v_mfma_f32_16x16x32_bf16 v[126:129], v[98:101], v[194:197], v[126:129]
	v_mfma_f32_16x16x32_bf16 v[122:125], v[158:161], v[194:197], v[122:125]
	v_mfma_f32_16x16x32_bf16 v[118:121], v[98:101], v[202:205], v[118:121]
	v_mfma_f32_16x16x32_bf16 v[114:117], v[158:161], v[202:205], v[114:117]
	v_mfma_f32_16x16x32_bf16 v[110:113], v[98:101], v[210:213], v[110:113]
	v_mfma_f32_16x16x32_bf16 v[106:109], v[158:161], v[210:213], v[106:109]
	v_mfma_f32_16x16x32_bf16 v[134:137], v[102:105], v[190:193], v[134:137]
	v_mfma_f32_16x16x32_bf16 v[130:133], v[162:165], v[190:193], v[130:133]
	v_mfma_f32_16x16x32_bf16 v[126:129], v[102:105], v[198:201], v[126:129]
	v_mfma_f32_16x16x32_bf16 v[122:125], v[162:165], v[198:201], v[122:125]
	v_mfma_f32_16x16x32_bf16 v[118:121], v[102:105], v[206:209], v[118:121]
	v_mfma_f32_16x16x32_bf16 v[114:117], v[162:165], v[206:209], v[114:117]
	v_mfma_f32_16x16x32_bf16 v[110:113], v[102:105], v[214:217], v[110:113]
	v_mfma_f32_16x16x32_bf16 v[106:109], v[162:165], v[214:217], v[106:109]
	s_setprio 0
	s_setprio 1
	v_mfma_f32_16x16x32_bf16 v[62:65], v[166:169], v[186:189], v[62:65]
	v_mfma_f32_16x16x32_bf16 v[58:61], v[174:177], v[186:189], v[58:61]
	v_mfma_f32_16x16x32_bf16 v[54:57], v[166:169], v[194:197], v[54:57]
	v_mfma_f32_16x16x32_bf16 v[50:53], v[174:177], v[194:197], v[50:53]
	v_mfma_f32_16x16x32_bf16 v[46:49], v[166:169], v[202:205], v[46:49]
	v_mfma_f32_16x16x32_bf16 v[42:45], v[174:177], v[202:205], v[42:45]
	v_mfma_f32_16x16x32_bf16 v[38:41], v[166:169], v[210:213], v[38:41]
	v_mfma_f32_16x16x32_bf16 v[34:37], v[174:177], v[210:213], v[34:37]
	v_mfma_f32_16x16x32_bf16 v[62:65], v[170:173], v[190:193], v[62:65]
	v_mfma_f32_16x16x32_bf16 v[58:61], v[182:185], v[190:193], v[58:61]
	v_mfma_f32_16x16x32_bf16 v[54:57], v[170:173], v[198:201], v[54:57]
	v_mfma_f32_16x16x32_bf16 v[50:53], v[182:185], v[198:201], v[50:53]
	v_mfma_f32_16x16x32_bf16 v[46:49], v[170:173], v[206:209], v[46:49]
	v_mfma_f32_16x16x32_bf16 v[42:45], v[182:185], v[206:209], v[42:45]
	v_mfma_f32_16x16x32_bf16 v[38:41], v[170:173], v[214:217], v[38:41]
	v_mfma_f32_16x16x32_bf16 v[34:37], v[182:185], v[214:217], v[34:37]
	s_setprio 0
	s_barrier
; #define PG8_STAGE(bufoff, gbase, voff) do { _Pragma("unroll") for (int _i = 0; _i < 2; ++_i) \
;         __builtin_amdgcn_global_load_lds((const unsigned*)((const char*)(gbase) + (voff)[_i]), (LAS unsigned*)(lds + (bufoff) + ldsw + _i * 8192), 16, 0, 0); } while (0)
; #define PG8_LDA(dst, b, h) do { _Pragma("unroll") for (int m = 0; m < 4; ++m) _Pragma("unroll") for (int k = 0; k < 2; ++k) dst[m][k] = *(const LAS bf16x8*)(lds + PG8_SA(b, h) + aoff + m * 2048 + k * 1024); } while (0)
; #define PG8_LDB(dst, b, h) do { _Pragma("unroll") for (int n = 0; n < 2; ++n) _Pragma("unroll") for (int k = 0; k < 2; ++k) dst[n][k] = *(const LAS bf16x8*)(lds + PG8_SB(b, h) + boff + n * 2048 + k * 1024); } while (0)
; #define PG8_MMA(ai, bj, At, Bt) do { __builtin_amdgcn_s_setprio(1); _Pragma("unroll") for (int m = 0; m < 4; ++m) _Pragma("unroll") for (int n = 0; n < 2; ++n) _Pragma("unroll") for (int k = 0; k < 2; ++k) \
;         acc[ai][bj][m][n] = __builtin_amdgcn_mfma_f32_16x16x32_bf16(Bt[n][k], At[m][k], acc[ai][bj][m][n], 0, 0, 0); __builtin_amdgcn_s_setprio(0); } while (0)
; #define PG8_WAIT_V(n) asm volatile("s_waitcnt vmcnt(" #n ")" ::: "memory")
; #define PG8_WAIT_L(n) asm volatile("s_waitcnt lgkmcnt(" #n ")" ::: "memory")
; #define PG8_BAR __builtin_amdgcn_s_barrier()
; #define PG8_SCHED __builtin_amdgcn_sched_barrier(0)
; template <class Epi>
; __device__ __forceinline__ void gemm_phase(LAS unsigned char* lds, const Gemm g, const StaticOrder& S, const Epi& E) {
;     ...
;             PG8_LDB(B0, 1, 0); PG8_LDB(B1, 1, 1); PG8_SCHED; PG8_LDA(At, 1, 0); PG8_STAGE(PG8_SA(0, 1), a2 + hA, voffA);
;             PG8_WAIT_V(8); PG8_WAIT_L(0); PG8_BAR; PG8_MMA(0, 0, At, B0); PG8_MMA(0, 1, At, B1); PG8_BAR; PG8_SCHED;
;             PG8_LDA(At, 1, 1); PG8_STAGE(PG8_SB(1, 0), b3, voffB); PG8_STAGE(PG8_SB(1, 1), b3 + hB, voffB); PG8_STAGE(PG8_SA(1, 0), a3, voffA);
;             PG8_WAIT_V(8); PG8_WAIT_L(0); PG8_BAR; PG8_MMA(1, 0, At, B0); PG8_MMA(1, 1, At, B1); PG8_BAR; PG8_SCHED;
;         }
	s_add_i32 s34, s71, s53
	v_lshl_add_u64 v[154:155], v[154:155], 0, s[88:89]
	s_mov_b32 m0, s34
	ds_read_b128 v[186:189], v157 offset:49152
	ds_read_b128 v[190:193], v157 offset:50176
	ds_read_b128 v[194:197], v157 offset:51200
	ds_read_b128 v[198:201], v157 offset:52224
	ds_read_b128 v[202:205], v157 offset:53248
	ds_read_b128 v[206:209], v157 offset:54272
	ds_read_b128 v[210:213], v157 offset:55296
	ds_read_b128 v[214:217], v157 offset:56320
	global_load_lds_dwordx4 v[154:155], off
	s_add_i32 m0, s34, 0x2000
	s_add_u32 s30, s30, 0x80080
	v_lshl_add_u64 v[154:155], v[178:179], 0, s[88:89]
	s_addc_u32 s31, s31, 0
	s_add_i32 s34, s73, s53
	global_load_lds_dwordx4 v[154:155], off
	v_lshl_add_u64 v[154:155], s[30:31], 0, v[140:141]
	s_mov_b32 m0, s34
	s_nop 0
	global_load_lds_dwordx4 v[154:155], off
	v_lshl_add_u64 v[154:155], s[30:31], 0, v[144:145]
	s_add_i32 m0, s34, 0x2000
	s_nop 0
	global_load_lds_dwordx4 v[154:155], off
	v_lshl_add_u64 v[154:155], v[218:219], 0, s[88:89]
	s_mov_b32 m0, s59
	s_nop 0
	global_load_lds_dwordx4 v[154:155], off
	v_lshl_add_u64 v[154:155], v[220:221], 0, s[88:89]
	s_mov_b32 m0, s60
	s_nop 0
	global_load_lds_dwordx4 v[154:155], off
	s_waitcnt vmcnt(8)
	s_waitcnt lgkmcnt(0)
	s_barrier
	s_setprio 1
	s_waitcnt lgkmcnt(0)
	v_mfma_f32_16x16x32_bf16 v[94:97], v[98:101], v[186:189], v[94:97]
	v_mfma_f32_16x16x32_bf16 v[90:93], v[158:161], v[186:189], v[90:93]
	v_mfma_f32_16x16x32_bf16 v[86:89], v[98:101], v[194:197], v[86:89]
	v_mfma_f32_16x16x32_bf16 v[82:85], v[158:161], v[194:197], v[82:85]
	v_mfma_f32_16x16x32_bf16 v[78:81], v[98:101], v[202:205], v[78:81]
	v_mfma_f32_16x16x32_bf16 v[74:77], v[158:161], v[202:205], v[74:77]
	v_mfma_f32_16x16x32_bf16 v[70:73], v[98:101], v[210:213], v[70:73]
	v_mfma_f32_16x16x32_bf16 v[66:69], v[158:161], v[210:213], v[66:69]
	v_mfma_f32_16x16x32_bf16 v[94:97], v[102:105], v[190:193], v[94:97]
	v_mfma_f32_16x16x32_bf16 v[90:93], v[162:165], v[190:193], v[90:93]
	v_mfma_f32_16x16x32_bf16 v[86:89], v[102:105], v[198:201], v[86:89]
	v_mfma_f32_16x16x32_bf16 v[82:85], v[162:165], v[198:201], v[82:85]
	v_mfma_f32_16x16x32_bf16 v[78:81], v[102:105], v[206:209], v[78:81]
	v_mfma_f32_16x16x32_bf16 v[74:77], v[162:165], v[206:209], v[74:77]
	v_mfma_f32_16x16x32_bf16 v[70:73], v[102:105], v[214:217], v[70:73]
	v_mfma_f32_16x16x32_bf16 v[66:69], v[162:165], v[214:217], v[66:69]
	s_setprio 0
	s_setprio 1
	v_mfma_f32_16x16x32_bf16 v[30:33], v[166:169], v[186:189], v[30:33]
	v_mfma_f32_16x16x32_bf16 v[26:29], v[174:177], v[186:189], v[26:29]
	v_mfma_f32_16x16x32_bf16 v[22:25], v[166:169], v[194:197], v[22:25]
	v_mfma_f32_16x16x32_bf16 v[18:21], v[174:177], v[194:197], v[18:21]
	v_mfma_f32_16x16x32_bf16 v[14:17], v[166:169], v[202:205], v[14:17]
	v_mfma_f32_16x16x32_bf16 v[10:13], v[174:177], v[202:205], v[10:13]
	v_mfma_f32_16x16x32_bf16 v[6:9], v[166:169], v[210:213], v[6:9]
	v_mfma_f32_16x16x32_bf16 v[2:5], v[174:177], v[210:213], v[2:5]
	v_mfma_f32_16x16x32_bf16 v[30:33], v[170:173], v[190:193], v[30:33]
	v_mfma_f32_16x16x32_bf16 v[26:29], v[182:185], v[190:193], v[26:29]
	v_mfma_f32_16x16x32_bf16 v[22:25], v[170:173], v[198:201], v[22:25]
	v_mfma_f32_16x16x32_bf16 v[18:21], v[182:185], v[198:201], v[18:21]
	v_mfma_f32_16x16x32_bf16 v[14:17], v[170:173], v[206:209], v[14:17]
	v_mfma_f32_16x16x32_bf16 v[10:13], v[182:185], v[206:209], v[10:13]
	v_mfma_f32_16x16x32_bf16 v[6:9], v[170:173], v[214:217], v[6:9]
	v_mfma_f32_16x16x32_bf16 v[2:5], v[182:185], v[214:217], v[2:5]
	s_setprio 0
	s_add_i32 s70, s70, 2
	s_add_u32 s28, s28, 0x100
	s_addc_u32 s29, s29, 0
	s_add_u32 s66, s66, 0x100
	s_addc_u32 s67, s67, 0
	s_add_u32 s30, s28, 0xfffc0080
	s_addc_u32 s31, s29, -1
	s_add_i32 s71, 0, 0x10000
	s_cmp_eq_u32 s70, 28
	s_cselect_b32 s35, s21, s31
	s_cselect_b32 s34, s27, s30
	s_cselect_b32 s31, s19, s67
	s_cselect_b32 s30, s65, s66
	s_add_i32 s73, 0, 0x14000
	s_cmp_gt_u32 s70, 29
	s_barrier
	s_cbranch_scc0 .Lrot_518
	s_and_b64 vcc, exec, s[16:17]
	s_cbranch_vccz .LBB0_521
	s_barrier

; #define PG8_STAGE(bufoff, gbase, voff) do { _Pragma("unroll") for (int _i = 0; _i < 2; ++_i) \
;         __builtin_amdgcn_global_load_lds((const unsigned*)((const char*)(gbase) + (voff)[_i]), (LAS unsigned*)(lds + (bufoff) + ldsw + _i * 8192), 16, 0, 0); } while (0)
; #define PG8_LDA(dst, b, h) do { _Pragma("unroll") for (int m = 0; m < 4; ++m) _Pragma("unroll") for (int k = 0; k < 2; ++k) dst[m][k] = *(const LAS bf16x8*)(lds + PG8_SA(b, h) + aoff + m * 2048 + k * 1024); } while (0)
; #define PG8_LDB(dst, b, h) do { _Pragma("unroll") for (int n = 0; n < 2; ++n) _Pragma("unroll") for (int k = 0; k < 2; ++k) dst[n][k] = *(const LAS bf16x8*)(lds + PG8_SB(b, h) + boff + n * 2048 + k * 1024); } while (0)
; #define PG8_MMA(ai, bj, At, Bt) do { __builtin_amdgcn_s_setprio(1); _Pragma("unroll") for (int m = 0; m < 4; ++m) _Pragma("unroll") for (int n = 0; n < 2; ++n) _Pragma("unroll") for (int k = 0; k < 2; ++k) \
;         acc[ai][bj][m][n] = __builtin_amdgcn_mfma_f32_16x16x32_bf16(Bt[n][k], At[m][k], acc[ai][bj][m][n], 0, 0, 0); __builtin_amdgcn_s_setprio(0); } while (0)
; #define PG8_WAIT_V(n) asm volatile("s_waitcnt vmcnt(" #n ")" ::: "memory")
; #define PG8_WAIT_L(n) asm volatile("s_waitcnt lgkmcnt(" #n ")" ::: "memory")
; #define PG8_BAR __builtin_amdgcn_s_barrier()
; #define PG8_SCHED __builtin_amdgcn_sched_barrier(0)
; template <class Epi>
; __device__ __forceinline__ void gemm_phase(LAS unsigned char* lds, const Gemm g, const StaticOrder& S, const Epi& E) {
;     ...
;             PG8_LDB(B0, 0, 0); PG8_LDB(B1, 0, 1); PG8_SCHED; PG8_LDA(At, 0, 0); PG8_STAGE(PG8_SA(1, 1), a1 + hA, voffA);
;             PG8_WAIT_V(8); PG8_WAIT_L(0); PG8_BAR; PG8_MMA(0, 0, At, B0); PG8_MMA(0, 1, At, B1); PG8_BAR; PG8_SCHED;
;             PG8_LDA(At, 0, 1); PG8_STAGE(PG8_SB(0, 0), b2, voffB); PG8_STAGE(PG8_SB(0, 1), b2 + hB, voffB); PG8_STAGE(PG8_SA(0, 0), a2, voffA);
;             PG8_WAIT_V(8); PG8_WAIT_L(0); PG8_BAR; PG8_MMA(1, 0, At, B0); PG8_MMA(1, 1, At, B1); PG8_BAR; PG8_SCHED;
.Lrot_1398:
	v_add_u32_e32 v158, s35, v180
	v_add_u32_e32 v174, s64, v180
	ds_read_b128 v[146:149], v158
	ds_read_b128 v[150:153], v158 offset:1024
	ds_read_b128 v[154:157], v158 offset:2048
	ds_read_b128 v[158:161], v158 offset:3072
	ds_read_b128 v[162:165], v174
	ds_read_b128 v[166:169], v174 offset:1024
	ds_read_b128 v[170:173], v174 offset:2048
	ds_read_b128 v[174:177], v174 offset:3072
	v_lshl_add_u64 v[178:179], s[8:9], 0, v[142:143]
	s_add_i32 m0, s51, 0xc000
	ds_read_b128 v[182:185], v211
	ds_read_b128 v[186:189], v211 offset:1024
	ds_read_b128 v[190:193], v211 offset:2048
	ds_read_b128 v[194:197], v211 offset:3072
	ds_read_b128 v[198:201], v211 offset:4096
	ds_read_b128 v[202:205], v211 offset:5120
	ds_read_b128 v[216:219], v211 offset:6144
	ds_read_b128 v[232:235], v211 offset:7168
	global_load_lds_dwordx4 v[178:179], off
	v_lshl_add_u64 v[178:179], s[8:9], 0, v[144:145]
	s_add_i32 m0, s51, 0xe000
	s_nop 0
	global_load_lds_dwordx4 v[178:179], off
	s_waitcnt vmcnt(8)
	s_waitcnt lgkmcnt(0)
	s_barrier
	s_setprio 1
	s_waitcnt lgkmcnt(0)
	v_mfma_f32_16x16x32_bf16 v[126:129], v[146:149], v[182:185], v[126:129]
	v_mfma_f32_16x16x32_bf16 v[122:125], v[154:157], v[182:185], v[122:125]
	v_mfma_f32_16x16x32_bf16 v[110:113], v[146:149], v[190:193], v[110:113]
	v_mfma_f32_16x16x32_bf16 v[106:109], v[154:157], v[190:193], v[106:109]
	v_mfma_f32_16x16x32_bf16 v[94:97], v[146:149], v[198:201], v[94:97]
	v_mfma_f32_16x16x32_bf16 v[90:93], v[154:157], v[198:201], v[90:93]
	v_mfma_f32_16x16x32_bf16 v[78:81], v[146:149], v[216:219], v[78:81]
	v_mfma_f32_16x16x32_bf16 v[74:77], v[154:157], v[216:219], v[74:77]
	v_mfma_f32_16x16x32_bf16 v[126:129], v[150:153], v[186:189], v[126:129]
	v_mfma_f32_16x16x32_bf16 v[122:125], v[158:161], v[186:189], v[122:125]
	v_mfma_f32_16x16x32_bf16 v[110:113], v[150:153], v[194:197], v[110:113]
	v_mfma_f32_16x16x32_bf16 v[106:109], v[158:161], v[194:197], v[106:109]
	v_mfma_f32_16x16x32_bf16 v[94:97], v[150:153], v[202:205], v[94:97]
	v_mfma_f32_16x16x32_bf16 v[90:93], v[158:161], v[202:205], v[90:93]
	v_mfma_f32_16x16x32_bf16 v[78:81], v[150:153], v[232:235], v[78:81]
	v_mfma_f32_16x16x32_bf16 v[74:77], v[158:161], v[232:235], v[74:77]
	s_setprio 0
	s_setprio 1
	v_mfma_f32_16x16x32_bf16 v[118:121], v[162:165], v[182:185], v[118:121]
	v_mfma_f32_16x16x32_bf16 v[114:117], v[170:173], v[182:185], v[114:117]
	v_mfma_f32_16x16x32_bf16 v[102:105], v[162:165], v[190:193], v[102:105]
	v_mfma_f32_16x16x32_bf16 v[98:101], v[170:173], v[190:193], v[98:101]
	v_mfma_f32_16x16x32_bf16 v[86:89], v[162:165], v[198:201], v[86:89]
	v_mfma_f32_16x16x32_bf16 v[82:85], v[170:173], v[198:201], v[82:85]
	v_mfma_f32_16x16x32_bf16 v[70:73], v[162:165], v[216:219], v[70:73]
	v_mfma_f32_16x16x32_bf16 v[66:69], v[170:173], v[216:219], v[66:69]
	v_mfma_f32_16x16x32_bf16 v[118:121], v[166:169], v[186:189], v[118:121]
	v_mfma_f32_16x16x32_bf16 v[114:117], v[174:177], v[186:189], v[114:117]
	v_mfma_f32_16x16x32_bf16 v[102:105], v[166:169], v[194:197], v[102:105]
	v_mfma_f32_16x16x32_bf16 v[98:101], v[174:177], v[194:197], v[98:101]
	v_mfma_f32_16x16x32_bf16 v[86:89], v[166:169], v[202:205], v[86:89]
	v_mfma_f32_16x16x32_bf16 v[82:85], v[174:177], v[202:205], v[82:85]
	v_mfma_f32_16x16x32_bf16 v[70:73], v[166:169], v[232:235], v[70:73]
	v_mfma_f32_16x16x32_bf16 v[66:69], v[174:177], v[232:235], v[66:69]
	s_setprio 0
	s_barrier
	s_add_i32 s35, s35, s50
	v_lshl_add_u64 v[178:179], s[10:11], 0, v[132:133]
	s_mov_b32 m0, s35
	ds_read_b128 v[182:185], v211 offset:16384
	ds_read_b128 v[186:189], v211 offset:17408
	ds_read_b128 v[190:193], v211 offset:18432
	ds_read_b128 v[194:197], v211 offset:19456
	ds_read_b128 v[198:201], v211 offset:20480
	ds_read_b128 v[202:205], v211 offset:21504
	ds_read_b128 v[216:219], v211 offset:22528
	ds_read_b128 v[232:235], v211 offset:23552
	global_load_lds_dwordx4 v[178:179], off
	s_add_i32 m0, s35, 0x2000
	s_add_u32 s42, s10, 0x40000
	v_lshl_add_u64 v[206:207], s[10:11], 0, v[136:137]
	s_addc_u32 s43, s11, 0
	s_add_i32 s35, s64, s50
	global_load_lds_dwordx4 v[206:207], off
	v_lshl_add_u64 v[220:221], s[42:43], 0, v[132:133]
	s_mov_b32 m0, s35
	v_lshl_add_u64 v[236:237], s[40:41], 0, v[134:135]
	global_load_lds_dwordx4 v[220:221], off
	v_lshl_add_u64 v[220:221], s[42:43], 0, v[136:137]
	s_add_i32 m0, s35, 0x2000
	s_nop 0
	global_load_lds_dwordx4 v[220:221], off
	v_lshl_add_u64 v[220:221], s[40:41], 0, v[130:131]
	s_mov_b32 m0, s51
	s_nop 0
	global_load_lds_dwordx4 v[220:221], off
	s_mov_b32 m0, s52
	s_nop 0
	global_load_lds_dwordx4 v[236:237], off
	s_waitcnt vmcnt(8)
	s_waitcnt lgkmcnt(0)
	s_barrier
; #define PG8_STAGE(bufoff, gbase, voff) do { _Pragma("unroll") for (int _i = 0; _i < 2; ++_i) \
;         __builtin_amdgcn_global_load_lds((const unsigned*)((const char*)(gbase) + (voff)[_i]), (LAS unsigned*)(lds + (bufoff) + ldsw + _i * 8192), 16, 0, 0); } while (0)
; #define PG8_LDA(dst, b, h) do { _Pragma("unroll") for (int m = 0; m < 4; ++m) _Pragma("unroll") for (int k = 0; k < 2; ++k) dst[m][k] = *(const LAS bf16x8*)(lds + PG8_SA(b, h) + aoff + m * 2048 + k * 1024); } while (0)
; #define PG8_LDB(dst, b, h) do { _Pragma("unroll") for (int n = 0; n < 2; ++n) _Pragma("unroll") for (int k = 0; k < 2; ++k) dst[n][k] = *(const LAS bf16x8*)(lds + PG8_SB(b, h) + boff + n * 2048 + k * 1024); } while (0)
; #define PG8_MMA(ai, bj, At, Bt) do { __builtin_amdgcn_s_setprio(1); _Pragma("unroll") for (int m = 0; m < 4; ++m) _Pragma("unroll") for (int n = 0; n < 2; ++n) _Pragma("unroll") for (int k = 0; k < 2; ++k) \
;         acc[ai][bj][m][n] = __builtin_amdgcn_mfma_f32_16x16x32_bf16(Bt[n][k], At[m][k], acc[ai][bj][m][n], 0, 0, 0); __builtin_amdgcn_s_setprio(0); } while (0)
; #define PG8_WAIT_V(n) asm volatile("s_waitcnt vmcnt(" #n ")" ::: "memory")
; #define PG8_WAIT_L(n) asm volatile("s_waitcnt lgkmcnt(" #n ")" ::: "memory")
; #define PG8_BAR __builtin_amdgcn_s_barrier()
; #define PG8_SCHED __builtin_amdgcn_sched_barrier(0)
; template <class Epi>
; __device__ __forceinline__ void gemm_phase(LAS unsigned char* lds, const Gemm g, const StaticOrder& S, const Epi& E) {
;     ...
;             PG8_WAIT_V(8); PG8_WAIT_L(0); PG8_BAR; PG8_MMA(1, 0, At, B0); PG8_MMA(1, 1, At, B1); PG8_BAR; PG8_SCHED;
;             PG8_LDB(B0, 1, 0); PG8_LDB(B1, 1, 1); PG8_SCHED; PG8_LDA(At, 1, 0); PG8_STAGE(PG8_SA(0, 1), a2 + hA, voffA);
;             PG8_WAIT_V(8); PG8_WAIT_L(0); PG8_BAR; PG8_MMA(0, 0, At, B0); PG8_MMA(0, 1, At, B1); PG8_BAR; PG8_SCHED;
	s_setprio 1
	s_waitcnt lgkmcnt(0)
	v_mfma_f32_16x16x32_bf16 v[62:65], v[146:149], v[182:185], v[62:65]
	v_mfma_f32_16x16x32_bf16 v[58:61], v[154:157], v[182:185], v[58:61]
	v_mfma_f32_16x16x32_bf16 v[46:49], v[146:149], v[190:193], v[46:49]
	v_mfma_f32_16x16x32_bf16 v[42:45], v[154:157], v[190:193], v[42:45]
	v_mfma_f32_16x16x32_bf16 v[30:33], v[146:149], v[198:201], v[30:33]
	v_mfma_f32_16x16x32_bf16 v[26:29], v[154:157], v[198:201], v[26:29]
	v_mfma_f32_16x16x32_bf16 v[14:17], v[146:149], v[216:219], v[14:17]
	v_mfma_f32_16x16x32_bf16 v[10:13], v[154:157], v[216:219], v[10:13]
	v_mfma_f32_16x16x32_bf16 v[62:65], v[150:153], v[186:189], v[62:65]
	v_mfma_f32_16x16x32_bf16 v[58:61], v[158:161], v[186:189], v[58:61]
	v_mfma_f32_16x16x32_bf16 v[46:49], v[150:153], v[194:197], v[46:49]
	v_mfma_f32_16x16x32_bf16 v[42:45], v[158:161], v[194:197], v[42:45]
	v_mfma_f32_16x16x32_bf16 v[30:33], v[150:153], v[202:205], v[30:33]
	v_mfma_f32_16x16x32_bf16 v[26:29], v[158:161], v[202:205], v[26:29]
	v_mfma_f32_16x16x32_bf16 v[14:17], v[150:153], v[232:235], v[14:17]
	v_mfma_f32_16x16x32_bf16 v[10:13], v[158:161], v[232:235], v[10:13]
	s_setprio 0
	s_setprio 1
	v_mfma_f32_16x16x32_bf16 v[54:57], v[162:165], v[182:185], v[54:57]
	v_mfma_f32_16x16x32_bf16 v[50:53], v[170:173], v[182:185], v[50:53]
	v_mfma_f32_16x16x32_bf16 v[38:41], v[162:165], v[190:193], v[38:41]
	v_mfma_f32_16x16x32_bf16 v[34:37], v[170:173], v[190:193], v[34:37]
	v_mfma_f32_16x16x32_bf16 v[22:25], v[162:165], v[198:201], v[22:25]
	v_mfma_f32_16x16x32_bf16 v[18:21], v[170:173], v[198:201], v[18:21]
	v_mfma_f32_16x16x32_bf16 v[6:9], v[162:165], v[216:219], v[6:9]
	v_mfma_f32_16x16x32_bf16 v[2:5], v[170:173], v[216:219], v[2:5]
	v_mfma_f32_16x16x32_bf16 v[54:57], v[166:169], v[186:189], v[54:57]
	v_mfma_f32_16x16x32_bf16 v[50:53], v[174:177], v[186:189], v[50:53]
	v_mfma_f32_16x16x32_bf16 v[38:41], v[166:169], v[194:197], v[38:41]
	v_mfma_f32_16x16x32_bf16 v[34:37], v[174:177], v[194:197], v[34:37]
	v_mfma_f32_16x16x32_bf16 v[22:25], v[166:169], v[202:205], v[22:25]
	v_mfma_f32_16x16x32_bf16 v[18:21], v[174:177], v[202:205], v[18:21]
	v_mfma_f32_16x16x32_bf16 v[6:9], v[166:169], v[232:235], v[6:9]
	v_mfma_f32_16x16x32_bf16 v[2:5], v[174:177], v[232:235], v[2:5]
	s_setprio 0
	s_barrier
	s_add_i32 s35, 0, 0x18000
	s_add_i32 s42, 0, 0x1c000
	v_add_u32_e32 v158, s35, v180
	v_add_u32_e32 v174, s42, v180
	ds_read_b128 v[146:149], v158
	ds_read_b128 v[150:153], v158 offset:1024
	ds_read_b128 v[154:157], v158 offset:2048
	ds_read_b128 v[158:161], v158 offset:3072
	ds_read_b128 v[162:165], v174
	ds_read_b128 v[166:169], v174 offset:1024
	ds_read_b128 v[170:173], v174 offset:2048
	ds_read_b128 v[174:177], v174 offset:3072
	s_add_u32 s40, s40, 0x40000
	s_addc_u32 s41, s41, 0
	s_mov_b32 m0, s53
	v_lshl_add_u64 v[238:239], s[40:41], 0, v[130:131]
	ds_read_b128 v[182:185], v211 offset:32768
	ds_read_b128 v[186:189], v211 offset:33792
	ds_read_b128 v[190:193], v211 offset:34816
	ds_read_b128 v[194:197], v211 offset:35840
	ds_read_b128 v[198:201], v211 offset:36864
	ds_read_b128 v[202:205], v211 offset:37888
	ds_read_b128 v[216:219], v211 offset:38912
	ds_read_b128 v[232:235], v211 offset:39936
	global_load_lds_dwordx4 v[238:239], off
	v_lshl_add_u64 v[238:239], s[40:41], 0, v[134:135]
	s_mov_b32 m0, s54
	s_nop 0
	global_load_lds_dwordx4 v[238:239], off
	s_waitcnt vmcnt(8)
	s_waitcnt lgkmcnt(0)
	s_barrier
	s_setprio 1
	s_waitcnt lgkmcnt(0)
	v_mfma_f32_16x16x32_bf16 v[126:129], v[146:149], v[182:185], v[126:129]
	v_mfma_f32_16x16x32_bf16 v[122:125], v[154:157], v[182:185], v[122:125]
	v_mfma_f32_16x16x32_bf16 v[110:113], v[146:149], v[190:193], v[110:113]
	v_mfma_f32_16x16x32_bf16 v[106:109], v[154:157], v[190:193], v[106:109]
	v_mfma_f32_16x16x32_bf16 v[94:97], v[146:149], v[198:201], v[94:97]
	v_mfma_f32_16x16x32_bf16 v[90:93], v[154:157], v[198:201], v[90:93]
	v_mfma_f32_16x16x32_bf16 v[78:81], v[146:149], v[216:219], v[78:81]
	v_mfma_f32_16x16x32_bf16 v[74:77], v[154:157], v[216:219], v[74:77]
	v_mfma_f32_16x16x32_bf16 v[126:129], v[150:153], v[186:189], v[126:129]
	v_mfma_f32_16x16x32_bf16 v[122:125], v[158:161], v[186:189], v[122:125]
	v_mfma_f32_16x16x32_bf16 v[110:113], v[150:153], v[194:197], v[110:113]
	v_mfma_f32_16x16x32_bf16 v[106:109], v[158:161], v[194:197], v[106:109]
	v_mfma_f32_16x16x32_bf16 v[94:97], v[150:153], v[202:205], v[94:97]
	v_mfma_f32_16x16x32_bf16 v[90:93], v[158:161], v[202:205], v[90:93]
	v_mfma_f32_16x16x32_bf16 v[78:81], v[150:153], v[232:235], v[78:81]
	v_mfma_f32_16x16x32_bf16 v[74:77], v[158:161], v[232:235], v[74:77]
	s_setprio 0
	s_setprio 1
	v_mfma_f32_16x16x32_bf16 v[118:121], v[162:165], v[182:185], v[118:121]
	v_mfma_f32_16x16x32_bf16 v[114:117], v[170:173], v[182:185], v[114:117]
	v_mfma_f32_16x16x32_bf16 v[102:105], v[162:165], v[190:193], v[102:105]
	v_mfma_f32_16x16x32_bf16 v[98:101], v[170:173], v[190:193], v[98:101]
	v_mfma_f32_16x16x32_bf16 v[86:89], v[162:165], v[198:201], v[86:89]
	v_mfma_f32_16x16x32_bf16 v[82:85], v[170:173], v[198:201], v[82:85]
	v_mfma_f32_16x16x32_bf16 v[70:73], v[162:165], v[216:219], v[70:73]
	v_mfma_f32_16x16x32_bf16 v[66:69], v[170:173], v[216:219], v[66:69]
	v_mfma_f32_16x16x32_bf16 v[118:121], v[166:169], v[186:189], v[118:121]
	v_mfma_f32_16x16x32_bf16 v[114:117], v[174:177], v[186:189], v[114:117]
	v_mfma_f32_16x16x32_bf16 v[102:105], v[166:169], v[194:197], v[102:105]
	v_mfma_f32_16x16x32_bf16 v[98:101], v[174:177], v[194:197], v[98:101]
	v_mfma_f32_16x16x32_bf16 v[86:89], v[166:169], v[202:205], v[86:89]
	v_mfma_f32_16x16x32_bf16 v[82:85], v[174:177], v[202:205], v[82:85]
	v_mfma_f32_16x16x32_bf16 v[70:73], v[166:169], v[232:235], v[70:73]
	v_mfma_f32_16x16x32_bf16 v[66:69], v[174:177], v[232:235], v[66:69]
	s_setprio 0
	s_barrier
; #define PG8_STAGE(bufoff, gbase, voff) do { _Pragma("unroll") for (int _i = 0; _i < 2; ++_i) \
;         __builtin_amdgcn_global_load_lds((const unsigned*)((const char*)(gbase) + (voff)[_i]), (LAS unsigned*)(lds + (bufoff) + ldsw + _i * 8192), 16, 0, 0); } while (0)
; #define PG8_LDA(dst, b, h) do { _Pragma("unroll") for (int m = 0; m < 4; ++m) _Pragma("unroll") for (int k = 0; k < 2; ++k) dst[m][k] = *(const LAS bf16x8*)(lds + PG8_SA(b, h) + aoff + m * 2048 + k * 1024); } while (0)
; #define PG8_MMA(ai, bj, At, Bt) do { __builtin_amdgcn_s_setprio(1); _Pragma("unroll") for (int m = 0; m < 4; ++m) _Pragma("unroll") for (int n = 0; n < 2; ++n) _Pragma("unroll") for (int k = 0; k < 2; ++k) \
;         acc[ai][bj][m][n] = __builtin_amdgcn_mfma_f32_16x16x32_bf16(Bt[n][k], At[m][k], acc[ai][bj][m][n], 0, 0, 0); __builtin_amdgcn_s_setprio(0); } while (0)
; #define PG8_WAIT_V(n) asm volatile("s_waitcnt vmcnt(" #n ")" ::: "memory")
; #define PG8_WAIT_L(n) asm volatile("s_waitcnt lgkmcnt(" #n ")" ::: "memory")
; #define PG8_BAR __builtin_amdgcn_s_barrier()
; #define PG8_SCHED __builtin_amdgcn_sched_barrier(0)
; template <class Epi>
; __device__ __forceinline__ void gemm_phase(LAS unsigned char* lds, const Gemm g, const StaticOrder& S, const Epi& E) {
;     ...
;         for (int t = 0; t < nt; t += 2) {
;             const bool last = (t == nt - 2);
;             const char* a1 = cA + (size_t)(t + 1) * kstep;
;             const char* a2 = last ? nA : cA + (size_t)(t + 2) * kstep; const char* b2 = last ? nB : cB + (size_t)(t + 2) * kstep;
;             const char* a3 = a2 + kstep; const char* b3 = b2 + kstep;
;     ...
;             PG8_LDA(At, 1, 1); PG8_STAGE(PG8_SB(1, 0), b3, voffB); PG8_STAGE(PG8_SB(1, 1), b3 + hB, voffB); PG8_STAGE(PG8_SA(1, 0), a3, voffA);
;             PG8_WAIT_V(8); PG8_WAIT_L(0); PG8_BAR; PG8_MMA(1, 0, At, B0); PG8_MMA(1, 1, At, B1); PG8_BAR; PG8_SCHED;
	s_add_i32 s35, s35, s50
	v_lshl_add_u64 v[178:179], v[178:179], 0, s[88:89]
	s_mov_b32 m0, s35
	ds_read_b128 v[182:185], v211 offset:49152
	ds_read_b128 v[186:189], v211 offset:50176
	ds_read_b128 v[190:193], v211 offset:51200
	ds_read_b128 v[194:197], v211 offset:52224
	ds_read_b128 v[198:201], v211 offset:53248
	ds_read_b128 v[202:205], v211 offset:54272
	ds_read_b128 v[216:219], v211 offset:55296
	ds_read_b128 v[232:235], v211 offset:56320
	global_load_lds_dwordx4 v[178:179], off
	s_add_i32 m0, s35, 0x2000
	s_add_u32 s10, s10, 0x40080
	v_lshl_add_u64 v[178:179], v[206:207], 0, s[88:89]
	s_addc_u32 s11, s11, 0
	s_add_i32 s35, s42, s50
	global_load_lds_dwordx4 v[178:179], off
	v_lshl_add_u64 v[178:179], s[10:11], 0, v[132:133]
	s_mov_b32 m0, s35
	s_nop 0
	global_load_lds_dwordx4 v[178:179], off
	v_lshl_add_u64 v[178:179], s[10:11], 0, v[136:137]
	s_add_i32 m0, s35, 0x2000
	s_nop 0
	global_load_lds_dwordx4 v[178:179], off
	v_lshl_add_u64 v[178:179], v[220:221], 0, s[88:89]
	s_mov_b32 m0, s55
	s_nop 0
	global_load_lds_dwordx4 v[178:179], off
	v_lshl_add_u64 v[178:179], v[236:237], 0, s[88:89]
	s_mov_b32 m0, s56
	s_nop 0
	global_load_lds_dwordx4 v[178:179], off
	s_waitcnt vmcnt(8)
	s_waitcnt lgkmcnt(0)
	s_barrier
	s_setprio 1
	s_waitcnt lgkmcnt(0)
	v_mfma_f32_16x16x32_bf16 v[62:65], v[146:149], v[182:185], v[62:65]
	v_mfma_f32_16x16x32_bf16 v[58:61], v[154:157], v[182:185], v[58:61]
	v_mfma_f32_16x16x32_bf16 v[46:49], v[146:149], v[190:193], v[46:49]
	v_mfma_f32_16x16x32_bf16 v[42:45], v[154:157], v[190:193], v[42:45]
	v_mfma_f32_16x16x32_bf16 v[30:33], v[146:149], v[198:201], v[30:33]
	v_mfma_f32_16x16x32_bf16 v[26:29], v[154:157], v[198:201], v[26:29]
	v_mfma_f32_16x16x32_bf16 v[14:17], v[146:149], v[216:219], v[14:17]
	v_mfma_f32_16x16x32_bf16 v[10:13], v[154:157], v[216:219], v[10:13]
	v_mfma_f32_16x16x32_bf16 v[62:65], v[150:153], v[186:189], v[62:65]
	v_mfma_f32_16x16x32_bf16 v[58:61], v[158:161], v[186:189], v[58:61]
	v_mfma_f32_16x16x32_bf16 v[46:49], v[150:153], v[194:197], v[46:49]
	v_mfma_f32_16x16x32_bf16 v[42:45], v[158:161], v[194:197], v[42:45]
	v_mfma_f32_16x16x32_bf16 v[30:33], v[150:153], v[202:205], v[30:33]
	v_mfma_f32_16x16x32_bf16 v[26:29], v[158:161], v[202:205], v[26:29]
	v_mfma_f32_16x16x32_bf16 v[14:17], v[150:153], v[232:235], v[14:17]
	v_mfma_f32_16x16x32_bf16 v[10:13], v[158:161], v[232:235], v[10:13]
	s_setprio 0
	s_setprio 1
	v_mfma_f32_16x16x32_bf16 v[54:57], v[162:165], v[182:185], v[54:57]
	v_mfma_f32_16x16x32_bf16 v[50:53], v[170:173], v[182:185], v[50:53]
	v_mfma_f32_16x16x32_bf16 v[38:41], v[162:165], v[190:193], v[38:41]
	v_mfma_f32_16x16x32_bf16 v[34:37], v[170:173], v[190:193], v[34:37]
	v_mfma_f32_16x16x32_bf16 v[22:25], v[162:165], v[198:201], v[22:25]
	v_mfma_f32_16x16x32_bf16 v[18:21], v[170:173], v[198:201], v[18:21]
	v_mfma_f32_16x16x32_bf16 v[6:9], v[162:165], v[216:219], v[6:9]
	v_mfma_f32_16x16x32_bf16 v[2:5], v[170:173], v[216:219], v[2:5]
	v_mfma_f32_16x16x32_bf16 v[54:57], v[166:169], v[186:189], v[54:57]
	v_mfma_f32_16x16x32_bf16 v[50:53], v[174:177], v[186:189], v[50:53]
	v_mfma_f32_16x16x32_bf16 v[38:41], v[166:169], v[194:197], v[38:41]
	v_mfma_f32_16x16x32_bf16 v[34:37], v[174:177], v[194:197], v[34:37]
	v_mfma_f32_16x16x32_bf16 v[22:25], v[166:169], v[202:205], v[22:25]
	v_mfma_f32_16x16x32_bf16 v[18:21], v[174:177], v[202:205], v[18:21]
	v_mfma_f32_16x16x32_bf16 v[6:9], v[166:169], v[232:235], v[6:9]
	v_mfma_f32_16x16x32_bf16 v[2:5], v[174:177], v[232:235], v[2:5]
	s_setprio 0
	s_add_i32 s31, s31, 2
	s_add_u32 s8, s8, 0x100
	s_addc_u32 s9, s9, 0
	s_add_u32 s27, s27, 0x100
	s_addc_u32 s29, s29, 0
	s_add_u32 s10, s8, 0xfffc0080
	s_addc_u32 s11, s9, -1
	s_add_i32 s35, 0, 0x10000
	s_cmp_eq_u32 s31, 12
	s_cselect_b32 s41, s37, s11
	s_cselect_b32 s40, s36, s10
	s_cselect_b32 s11, s39, s29
	s_cselect_b32 s10, s38, s27
	s_add_i32 s64, 0, 0x14000
	s_cmp_gt_u32 s31, 13
	s_barrier
	s_cbranch_scc0 .Lrot_1398
	s_and_b64 vcc, exec, s[16:17]
	s_cbranch_vccz .LBB0_1401
	s_barrier

; #define PG8_STAGE(bufoff, gbase, voff) do { _Pragma("unroll") for (int _i = 0; _i < 2; ++_i) \
;         __builtin_amdgcn_global_load_lds((const unsigned*)((const char*)(gbase) + (voff)[_i]), (LAS unsigned*)(lds + (bufoff) + ldsw + _i * 8192), 16, 0, 0); } while (0)
; #define PG8_LDA(dst, b, h) do { _Pragma("unroll") for (int m = 0; m < 4; ++m) _Pragma("unroll") for (int k = 0; k < 2; ++k) dst[m][k] = *(const LAS bf16x8*)(lds + PG8_SA(b, h) + aoff + m * 2048 + k * 1024); } while (0)
; #define PG8_LDB(dst, b, h) do { _Pragma("unroll") for (int n = 0; n < 2; ++n) _Pragma("unroll") for (int k = 0; k < 2; ++k) dst[n][k] = *(const LAS bf16x8*)(lds + PG8_SB(b, h) + boff + n * 2048 + k * 1024); } while (0)
; #define PG8_MMA(ai, bj, At, Bt) do { __builtin_amdgcn_s_setprio(1); _Pragma("unroll") for (int m = 0; m < 4; ++m) _Pragma("unroll") for (int n = 0; n < 2; ++n) _Pragma("unroll") for (int k = 0; k < 2; ++k) \
;         acc[ai][bj][m][n] = __builtin_amdgcn_mfma_f32_16x16x32_bf16(Bt[n][k], At[m][k], acc[ai][bj][m][n], 0, 0, 0); __builtin_amdgcn_s_setprio(0); } while (0)
; #define PG8_WAIT_V(n) asm volatile("s_waitcnt vmcnt(" #n ")" ::: "memory")
; #define PG8_WAIT_L(n) asm volatile("s_waitcnt lgkmcnt(" #n ")" ::: "memory")
; #define PG8_BAR __builtin_amdgcn_s_barrier()
; #define PG8_SCHED __builtin_amdgcn_sched_barrier(0)
; template <class Epi>
; __device__ __forceinline__ void gemm_phase(LAS unsigned char* lds, const Gemm g, const StaticOrder& S, const Epi& E) {
;     ...
;         for (int t = 0; t < nt; t += 2) {
;             const bool last = (t == nt - 2);
;             const char* a1 = cA + (size_t)(t + 1) * kstep;
;             const char* a2 = last ? nA : cA + (size_t)(t + 2) * kstep; const char* b2 = last ? nB : cB + (size_t)(t + 2) * kstep;
;             const char* a3 = a2 + kstep; const char* b3 = b2 + kstep;
;             PG8_LDB(B0, 0, 0); PG8_LDB(B1, 0, 1); PG8_SCHED; PG8_LDA(At, 0, 0); PG8_STAGE(PG8_SA(1, 1), a1 + hA, voffA);
;             PG8_WAIT_V(8); PG8_WAIT_L(0); PG8_BAR; PG8_MMA(0, 0, At, B0); PG8_MMA(0, 1, At, B1); PG8_BAR; PG8_SCHED;
;             PG8_LDA(At, 0, 1); PG8_STAGE(PG8_SB(0, 0), b2, voffB); PG8_STAGE(PG8_SB(0, 1), b2 + hB, voffB); PG8_STAGE(PG8_SA(0, 0), a2, voffA);
;             PG8_WAIT_V(8); PG8_WAIT_L(0); PG8_BAR; PG8_MMA(1, 0, At, B0); PG8_MMA(1, 1, At, B1); PG8_BAR; PG8_SCHED;
.LBB0_1550:
	s_add_u32 s22, s20, 0xfffc0080
	s_addc_u32 s23, s21, -1
	s_add_i32 s51, 0, 0x10000
	s_cmp_eq_u32 s50, 12
	s_cselect_b32 s25, s15, s23
	s_cselect_b32 s24, s46, s22
	s_cselect_b32 s23, s13, s49
	s_cselect_b32 s22, s47, s48
	s_add_i32 s54, 0, 0x14000
.Lrot_1550:
	v_add_u32_e32 v142, s51, v143
	ds_read_b128 v[148:151], v142
	ds_read_b128 v[152:155], v142 offset:1024
	ds_read_b128 v[156:159], v142 offset:2048
	ds_read_b128 v[160:163], v142 offset:3072
	v_add_u32_e32 v142, s54, v143
	ds_read_b128 v[164:167], v142
	ds_read_b128 v[168:171], v142 offset:1024
	ds_read_b128 v[172:175], v142 offset:2048
	ds_read_b128 v[176:179], v142 offset:3072
	v_lshl_add_u64 v[214:215], s[20:21], 0, v[138:139]
	s_add_i32 m0, s34, 0xc000
	ds_read_b128 v[182:185], v147
	ds_read_b128 v[186:189], v147 offset:1024
	ds_read_b128 v[190:193], v147 offset:2048
	ds_read_b128 v[194:197], v147 offset:3072
	ds_read_b128 v[198:201], v147 offset:4096
	ds_read_b128 v[202:205], v147 offset:5120
	ds_read_b128 v[206:209], v147 offset:6144
	ds_read_b128 v[210:213], v147 offset:7168
	global_load_lds_dwordx4 v[214:215], off
	v_lshl_add_u64 v[214:215], s[20:21], 0, v[140:141]
	s_add_i32 m0, s34, 0xe000
	s_nop 0
	global_load_lds_dwordx4 v[214:215], off
	s_waitcnt vmcnt(8)
	s_waitcnt lgkmcnt(0)
	s_barrier
	s_setprio 1
	s_waitcnt lgkmcnt(0)
	v_mfma_f32_16x16x32_bf16 v[126:129], v[148:151], v[182:185], v[126:129]
	v_mfma_f32_16x16x32_bf16 v[122:125], v[156:159], v[182:185], v[122:125]
	v_mfma_f32_16x16x32_bf16 v[110:113], v[148:151], v[190:193], v[110:113]
	v_mfma_f32_16x16x32_bf16 v[106:109], v[156:159], v[190:193], v[106:109]
	v_mfma_f32_16x16x32_bf16 v[94:97], v[148:151], v[198:201], v[94:97]
	v_mfma_f32_16x16x32_bf16 v[90:93], v[156:159], v[198:201], v[90:93]
	v_mfma_f32_16x16x32_bf16 v[78:81], v[148:151], v[206:209], v[78:81]
	v_mfma_f32_16x16x32_bf16 v[74:77], v[156:159], v[206:209], v[74:77]
	v_mfma_f32_16x16x32_bf16 v[126:129], v[152:155], v[186:189], v[126:129]
	v_mfma_f32_16x16x32_bf16 v[122:125], v[160:163], v[186:189], v[122:125]
	v_mfma_f32_16x16x32_bf16 v[110:113], v[152:155], v[194:197], v[110:113]
	v_mfma_f32_16x16x32_bf16 v[106:109], v[160:163], v[194:197], v[106:109]
	v_mfma_f32_16x16x32_bf16 v[94:97], v[152:155], v[202:205], v[94:97]
	v_mfma_f32_16x16x32_bf16 v[90:93], v[160:163], v[202:205], v[90:93]
	v_mfma_f32_16x16x32_bf16 v[78:81], v[152:155], v[210:213], v[78:81]
	v_mfma_f32_16x16x32_bf16 v[74:77], v[160:163], v[210:213], v[74:77]
	s_setprio 0
	s_setprio 1
	v_mfma_f32_16x16x32_bf16 v[118:121], v[164:167], v[182:185], v[118:121]
	v_mfma_f32_16x16x32_bf16 v[114:117], v[172:175], v[182:185], v[114:117]
	v_mfma_f32_16x16x32_bf16 v[102:105], v[164:167], v[190:193], v[102:105]
	v_mfma_f32_16x16x32_bf16 v[98:101], v[172:175], v[190:193], v[98:101]
	v_mfma_f32_16x16x32_bf16 v[86:89], v[164:167], v[198:201], v[86:89]
	v_mfma_f32_16x16x32_bf16 v[82:85], v[172:175], v[198:201], v[82:85]
	v_mfma_f32_16x16x32_bf16 v[70:73], v[164:167], v[206:209], v[70:73]
	v_mfma_f32_16x16x32_bf16 v[66:69], v[172:175], v[206:209], v[66:69]
	v_mfma_f32_16x16x32_bf16 v[118:121], v[168:171], v[186:189], v[118:121]
	v_mfma_f32_16x16x32_bf16 v[114:117], v[176:179], v[186:189], v[114:117]
	v_mfma_f32_16x16x32_bf16 v[102:105], v[168:171], v[194:197], v[102:105]
	v_mfma_f32_16x16x32_bf16 v[98:101], v[176:179], v[194:197], v[98:101]
	v_mfma_f32_16x16x32_bf16 v[86:89], v[168:171], v[202:205], v[86:89]
	v_mfma_f32_16x16x32_bf16 v[82:85], v[176:179], v[202:205], v[82:85]
	v_mfma_f32_16x16x32_bf16 v[70:73], v[168:171], v[210:213], v[70:73]
	v_mfma_f32_16x16x32_bf16 v[66:69], v[176:179], v[210:213], v[66:69]
	s_setprio 0
	s_barrier
	s_add_i32 s51, s51, s31
	v_lshl_add_u64 v[214:215], s[22:23], 0, v[134:135]
	s_mov_b32 m0, s51
	ds_read_b128 v[182:185], v147 offset:16384
	ds_read_b128 v[186:189], v147 offset:17408
	ds_read_b128 v[190:193], v147 offset:18432
	ds_read_b128 v[194:197], v147 offset:19456
	ds_read_b128 v[198:201], v147 offset:20480
	ds_read_b128 v[202:205], v147 offset:21504
	ds_read_b128 v[206:209], v147 offset:22528
	ds_read_b128 v[210:213], v147 offset:23552
	global_load_lds_dwordx4 v[214:215], off
	s_add_i32 m0, s51, 0x2000
	s_add_u32 s52, s22, 0x40000
	v_lshl_add_u64 v[216:217], s[22:23], 0, v[130:131]
	s_addc_u32 s53, s23, 0
	s_add_i32 s51, s54, s31
	global_load_lds_dwordx4 v[216:217], off
	v_lshl_add_u64 v[218:219], s[52:53], 0, v[134:135]
	s_mov_b32 m0, s51
	v_lshl_add_u64 v[220:221], s[24:25], 0, v[132:133]
	global_load_lds_dwordx4 v[218:219], off
	v_lshl_add_u64 v[218:219], s[52:53], 0, v[130:131]
	s_add_i32 m0, s51, 0x2000
	s_nop 0
	global_load_lds_dwordx4 v[218:219], off
	v_lshl_add_u64 v[218:219], s[24:25], 0, v[136:137]
	s_mov_b32 m0, s34
	s_nop 0
	global_load_lds_dwordx4 v[218:219], off
	s_mov_b32 m0, s35
	s_nop 0
	global_load_lds_dwordx4 v[220:221], off
	s_waitcnt vmcnt(8)
	s_waitcnt lgkmcnt(0)
	s_barrier
; #define PG8_STAGE(bufoff, gbase, voff) do { _Pragma("unroll") for (int _i = 0; _i < 2; ++_i) \
;         __builtin_amdgcn_global_load_lds((const unsigned*)((const char*)(gbase) + (voff)[_i]), (LAS unsigned*)(lds + (bufoff) + ldsw + _i * 8192), 16, 0, 0); } while (0)
; #define PG8_LDA(dst, b, h) do { _Pragma("unroll") for (int m = 0; m < 4; ++m) _Pragma("unroll") for (int k = 0; k < 2; ++k) dst[m][k] = *(const LAS bf16x8*)(lds + PG8_SA(b, h) + aoff + m * 2048 + k * 1024); } while (0)
; #define PG8_LDB(dst, b, h) do { _Pragma("unroll") for (int n = 0; n < 2; ++n) _Pragma("unroll") for (int k = 0; k < 2; ++k) dst[n][k] = *(const LAS bf16x8*)(lds + PG8_SB(b, h) + boff + n * 2048 + k * 1024); } while (0)
; #define PG8_MMA(ai, bj, At, Bt) do { __builtin_amdgcn_s_setprio(1); _Pragma("unroll") for (int m = 0; m < 4; ++m) _Pragma("unroll") for (int n = 0; n < 2; ++n) _Pragma("unroll") for (int k = 0; k < 2; ++k) \
;         acc[ai][bj][m][n] = __builtin_amdgcn_mfma_f32_16x16x32_bf16(Bt[n][k], At[m][k], acc[ai][bj][m][n], 0, 0, 0); __builtin_amdgcn_s_setprio(0); } while (0)
; #define PG8_WAIT_V(n) asm volatile("s_waitcnt vmcnt(" #n ")" ::: "memory")
; #define PG8_WAIT_L(n) asm volatile("s_waitcnt lgkmcnt(" #n ")" ::: "memory")
; #define PG8_BAR __builtin_amdgcn_s_barrier()
; #define PG8_SCHED __builtin_amdgcn_sched_barrier(0)
; template <class Epi>
; __device__ __forceinline__ void gemm_phase(LAS unsigned char* lds, const Gemm g, const StaticOrder& S, const Epi& E) {
;     ...
;             PG8_WAIT_V(8); PG8_WAIT_L(0); PG8_BAR; PG8_MMA(1, 0, At, B0); PG8_MMA(1, 1, At, B1); PG8_BAR; PG8_SCHED;
;             PG8_LDB(B0, 1, 0); PG8_LDB(B1, 1, 1); PG8_SCHED; PG8_LDA(At, 1, 0); PG8_STAGE(PG8_SA(0, 1), a2 + hA, voffA);
;             PG8_WAIT_V(8); PG8_WAIT_L(0); PG8_BAR; PG8_MMA(0, 0, At, B0); PG8_MMA(0, 1, At, B1); PG8_BAR; PG8_SCHED;
	s_setprio 1
	s_waitcnt lgkmcnt(0)
	v_mfma_f32_16x16x32_bf16 v[62:65], v[148:151], v[182:185], v[62:65]
	v_mfma_f32_16x16x32_bf16 v[58:61], v[156:159], v[182:185], v[58:61]
	v_mfma_f32_16x16x32_bf16 v[46:49], v[148:151], v[190:193], v[46:49]
	v_mfma_f32_16x16x32_bf16 v[42:45], v[156:159], v[190:193], v[42:45]
	v_mfma_f32_16x16x32_bf16 v[30:33], v[148:151], v[198:201], v[30:33]
	v_mfma_f32_16x16x32_bf16 v[26:29], v[156:159], v[198:201], v[26:29]
	v_mfma_f32_16x16x32_bf16 v[14:17], v[148:151], v[206:209], v[14:17]
	v_mfma_f32_16x16x32_bf16 v[10:13], v[156:159], v[206:209], v[10:13]
	v_mfma_f32_16x16x32_bf16 v[62:65], v[152:155], v[186:189], v[62:65]
	v_mfma_f32_16x16x32_bf16 v[58:61], v[160:163], v[186:189], v[58:61]
	v_mfma_f32_16x16x32_bf16 v[46:49], v[152:155], v[194:197], v[46:49]
	v_mfma_f32_16x16x32_bf16 v[42:45], v[160:163], v[194:197], v[42:45]
	v_mfma_f32_16x16x32_bf16 v[30:33], v[152:155], v[202:205], v[30:33]
	v_mfma_f32_16x16x32_bf16 v[26:29], v[160:163], v[202:205], v[26:29]
	v_mfma_f32_16x16x32_bf16 v[14:17], v[152:155], v[210:213], v[14:17]
	v_mfma_f32_16x16x32_bf16 v[10:13], v[160:163], v[210:213], v[10:13]
	s_setprio 0
	s_setprio 1
	v_mfma_f32_16x16x32_bf16 v[54:57], v[164:167], v[182:185], v[54:57]
	v_mfma_f32_16x16x32_bf16 v[50:53], v[172:175], v[182:185], v[50:53]
	v_mfma_f32_16x16x32_bf16 v[38:41], v[164:167], v[190:193], v[38:41]
	v_mfma_f32_16x16x32_bf16 v[34:37], v[172:175], v[190:193], v[34:37]
	v_mfma_f32_16x16x32_bf16 v[22:25], v[164:167], v[198:201], v[22:25]
	v_mfma_f32_16x16x32_bf16 v[18:21], v[172:175], v[198:201], v[18:21]
	v_mfma_f32_16x16x32_bf16 v[6:9], v[164:167], v[206:209], v[6:9]
	v_mfma_f32_16x16x32_bf16 v[2:5], v[172:175], v[206:209], v[2:5]
	v_mfma_f32_16x16x32_bf16 v[54:57], v[168:171], v[186:189], v[54:57]
	v_mfma_f32_16x16x32_bf16 v[50:53], v[176:179], v[186:189], v[50:53]
	v_mfma_f32_16x16x32_bf16 v[38:41], v[168:171], v[194:197], v[38:41]
	v_mfma_f32_16x16x32_bf16 v[34:37], v[176:179], v[194:197], v[34:37]
	v_mfma_f32_16x16x32_bf16 v[22:25], v[168:171], v[202:205], v[22:25]
	v_mfma_f32_16x16x32_bf16 v[18:21], v[176:179], v[202:205], v[18:21]
	v_mfma_f32_16x16x32_bf16 v[6:9], v[168:171], v[210:213], v[6:9]
	v_mfma_f32_16x16x32_bf16 v[2:5], v[176:179], v[210:213], v[2:5]
	s_setprio 0
	s_barrier
	s_add_i32 s51, 0, 0x18000
	v_add_u32_e32 v142, s51, v143
	s_add_i32 s52, 0, 0x1c000
	ds_read_b128 v[148:151], v142
	ds_read_b128 v[152:155], v142 offset:1024
	ds_read_b128 v[156:159], v142 offset:2048
	ds_read_b128 v[160:163], v142 offset:3072
	v_add_u32_e32 v142, s52, v143
	ds_read_b128 v[164:167], v142
	ds_read_b128 v[168:171], v142 offset:1024
	ds_read_b128 v[172:175], v142 offset:2048
	ds_read_b128 v[176:179], v142 offset:3072
	s_add_u32 s24, s24, 0x40000
	s_addc_u32 s25, s25, 0
	s_mov_b32 m0, s36
	v_lshl_add_u64 v[232:233], s[24:25], 0, v[136:137]
	ds_read_b128 v[182:185], v147 offset:32768
	ds_read_b128 v[186:189], v147 offset:33792
	ds_read_b128 v[190:193], v147 offset:34816
	ds_read_b128 v[194:197], v147 offset:35840
	ds_read_b128 v[198:201], v147 offset:36864
	ds_read_b128 v[202:205], v147 offset:37888
	ds_read_b128 v[206:209], v147 offset:38912
	ds_read_b128 v[210:213], v147 offset:39936
	global_load_lds_dwordx4 v[232:233], off
	v_lshl_add_u64 v[232:233], s[24:25], 0, v[132:133]
	s_mov_b32 m0, s37
	s_nop 0
	global_load_lds_dwordx4 v[232:233], off
	s_waitcnt vmcnt(8)
	s_waitcnt lgkmcnt(0)
	s_barrier
	s_setprio 1
	s_waitcnt lgkmcnt(0)
	v_mfma_f32_16x16x32_bf16 v[126:129], v[148:151], v[182:185], v[126:129]
	v_mfma_f32_16x16x32_bf16 v[122:125], v[156:159], v[182:185], v[122:125]
	v_mfma_f32_16x16x32_bf16 v[110:113], v[148:151], v[190:193], v[110:113]
	v_mfma_f32_16x16x32_bf16 v[106:109], v[156:159], v[190:193], v[106:109]
	v_mfma_f32_16x16x32_bf16 v[94:97], v[148:151], v[198:201], v[94:97]
	v_mfma_f32_16x16x32_bf16 v[90:93], v[156:159], v[198:201], v[90:93]
	v_mfma_f32_16x16x32_bf16 v[78:81], v[148:151], v[206:209], v[78:81]
	v_mfma_f32_16x16x32_bf16 v[74:77], v[156:159], v[206:209], v[74:77]
	v_mfma_f32_16x16x32_bf16 v[126:129], v[152:155], v[186:189], v[126:129]
	v_mfma_f32_16x16x32_bf16 v[122:125], v[160:163], v[186:189], v[122:125]
	v_mfma_f32_16x16x32_bf16 v[110:113], v[152:155], v[194:197], v[110:113]
	v_mfma_f32_16x16x32_bf16 v[106:109], v[160:163], v[194:197], v[106:109]
	v_mfma_f32_16x16x32_bf16 v[94:97], v[152:155], v[202:205], v[94:97]
	v_mfma_f32_16x16x32_bf16 v[90:93], v[160:163], v[202:205], v[90:93]
	v_mfma_f32_16x16x32_bf16 v[78:81], v[152:155], v[210:213], v[78:81]
	v_mfma_f32_16x16x32_bf16 v[74:77], v[160:163], v[210:213], v[74:77]
	s_setprio 0
	s_setprio 1
	v_mfma_f32_16x16x32_bf16 v[118:121], v[164:167], v[182:185], v[118:121]
	v_mfma_f32_16x16x32_bf16 v[114:117], v[172:175], v[182:185], v[114:117]
	v_mfma_f32_16x16x32_bf16 v[102:105], v[164:167], v[190:193], v[102:105]
	v_mfma_f32_16x16x32_bf16 v[98:101], v[172:175], v[190:193], v[98:101]
	v_mfma_f32_16x16x32_bf16 v[86:89], v[164:167], v[198:201], v[86:89]
	v_mfma_f32_16x16x32_bf16 v[82:85], v[172:175], v[198:201], v[82:85]
	v_mfma_f32_16x16x32_bf16 v[70:73], v[164:167], v[206:209], v[70:73]
	v_mfma_f32_16x16x32_bf16 v[66:69], v[172:175], v[206:209], v[66:69]
	v_mfma_f32_16x16x32_bf16 v[118:121], v[168:171], v[186:189], v[118:121]
	v_mfma_f32_16x16x32_bf16 v[114:117], v[176:179], v[186:189], v[114:117]
	v_mfma_f32_16x16x32_bf16 v[102:105], v[168:171], v[194:197], v[102:105]
	v_mfma_f32_16x16x32_bf16 v[98:101], v[176:179], v[194:197], v[98:101]
	v_mfma_f32_16x16x32_bf16 v[86:89], v[168:171], v[202:205], v[86:89]
	v_mfma_f32_16x16x32_bf16 v[82:85], v[176:179], v[202:205], v[82:85]
	v_mfma_f32_16x16x32_bf16 v[70:73], v[168:171], v[210:213], v[70:73]
	v_mfma_f32_16x16x32_bf16 v[66:69], v[176:179], v[210:213], v[66:69]
	s_setprio 0
	s_barrier
; #define PG8_STAGE(bufoff, gbase, voff) do { _Pragma("unroll") for (int _i = 0; _i < 2; ++_i) \
;         __builtin_amdgcn_global_load_lds((const unsigned*)((const char*)(gbase) + (voff)[_i]), (LAS unsigned*)(lds + (bufoff) + ldsw + _i * 8192), 16, 0, 0); } while (0)
; #define PG8_LDA(dst, b, h) do { _Pragma("unroll") for (int m = 0; m < 4; ++m) _Pragma("unroll") for (int k = 0; k < 2; ++k) dst[m][k] = *(const LAS bf16x8*)(lds + PG8_SA(b, h) + aoff + m * 2048 + k * 1024); } while (0)
; #define PG8_MMA(ai, bj, At, Bt) do { __builtin_amdgcn_s_setprio(1); _Pragma("unroll") for (int m = 0; m < 4; ++m) _Pragma("unroll") for (int n = 0; n < 2; ++n) _Pragma("unroll") for (int k = 0; k < 2; ++k) \
;         acc[ai][bj][m][n] = __builtin_amdgcn_mfma_f32_16x16x32_bf16(Bt[n][k], At[m][k], acc[ai][bj][m][n], 0, 0, 0); __builtin_amdgcn_s_setprio(0); } while (0)
; #define PG8_WAIT_V(n) asm volatile("s_waitcnt vmcnt(" #n ")" ::: "memory")
; #define PG8_WAIT_L(n) asm volatile("s_waitcnt lgkmcnt(" #n ")" ::: "memory")
; #define PG8_BAR __builtin_amdgcn_s_barrier()
; #define PG8_SCHED __builtin_amdgcn_sched_barrier(0)
; template <class Epi>
; __device__ __forceinline__ void gemm_phase(LAS unsigned char* lds, const Gemm g, const StaticOrder& S, const Epi& E) {
;     ...
;         for (int t = 0; t < nt; t += 2) {
;             const bool last = (t == nt - 2);
;             const char* a1 = cA + (size_t)(t + 1) * kstep;
;             const char* a2 = last ? nA : cA + (size_t)(t + 2) * kstep; const char* b2 = last ? nB : cB + (size_t)(t + 2) * kstep;
;             const char* a3 = a2 + kstep; const char* b3 = b2 + kstep;
;     ...
;             PG8_LDA(At, 1, 1); PG8_STAGE(PG8_SB(1, 0), b3, voffB); PG8_STAGE(PG8_SB(1, 1), b3 + hB, voffB); PG8_STAGE(PG8_SA(1, 0), a3, voffA);
;             PG8_WAIT_V(8); PG8_WAIT_L(0); PG8_BAR; PG8_MMA(1, 0, At, B0); PG8_MMA(1, 1, At, B1); PG8_BAR; PG8_SCHED;
	s_add_i32 s24, s51, s31
	v_lshl_add_u64 v[214:215], v[214:215], 0, s[88:89]
	s_mov_b32 m0, s24
	ds_read_b128 v[182:185], v147 offset:49152
	ds_read_b128 v[186:189], v147 offset:50176
	ds_read_b128 v[190:193], v147 offset:51200
	ds_read_b128 v[194:197], v147 offset:52224
	ds_read_b128 v[198:201], v147 offset:53248
	ds_read_b128 v[202:205], v147 offset:54272
	ds_read_b128 v[206:209], v147 offset:55296
	ds_read_b128 v[210:213], v147 offset:56320
	global_load_lds_dwordx4 v[214:215], off
	s_add_i32 m0, s24, 0x2000
	s_add_u32 s22, s22, 0x40080
	v_lshl_add_u64 v[214:215], v[216:217], 0, s[88:89]
	s_addc_u32 s23, s23, 0
	s_add_i32 s24, s52, s31
	global_load_lds_dwordx4 v[214:215], off
	v_lshl_add_u64 v[214:215], s[22:23], 0, v[134:135]
	s_mov_b32 m0, s24
	s_nop 0
	global_load_lds_dwordx4 v[214:215], off
	v_lshl_add_u64 v[214:215], s[22:23], 0, v[130:131]
	s_add_i32 m0, s24, 0x2000
	s_nop 0
	global_load_lds_dwordx4 v[214:215], off
	v_lshl_add_u64 v[214:215], v[218:219], 0, s[88:89]
	s_mov_b32 m0, s38
	s_nop 0
	global_load_lds_dwordx4 v[214:215], off
	v_lshl_add_u64 v[214:215], v[220:221], 0, s[88:89]
	s_mov_b32 m0, s39
	s_nop 0
	global_load_lds_dwordx4 v[214:215], off
	s_waitcnt vmcnt(8)
	s_waitcnt lgkmcnt(0)
	s_barrier
	s_setprio 1
	s_waitcnt lgkmcnt(0)
	v_mfma_f32_16x16x32_bf16 v[62:65], v[148:151], v[182:185], v[62:65]
	v_mfma_f32_16x16x32_bf16 v[58:61], v[156:159], v[182:185], v[58:61]
	v_mfma_f32_16x16x32_bf16 v[46:49], v[148:151], v[190:193], v[46:49]
	v_mfma_f32_16x16x32_bf16 v[42:45], v[156:159], v[190:193], v[42:45]
	v_mfma_f32_16x16x32_bf16 v[30:33], v[148:151], v[198:201], v[30:33]
	v_mfma_f32_16x16x32_bf16 v[26:29], v[156:159], v[198:201], v[26:29]
	v_mfma_f32_16x16x32_bf16 v[14:17], v[148:151], v[206:209], v[14:17]
	v_mfma_f32_16x16x32_bf16 v[10:13], v[156:159], v[206:209], v[10:13]
	v_mfma_f32_16x16x32_bf16 v[62:65], v[152:155], v[186:189], v[62:65]
	v_mfma_f32_16x16x32_bf16 v[58:61], v[160:163], v[186:189], v[58:61]
	v_mfma_f32_16x16x32_bf16 v[46:49], v[152:155], v[194:197], v[46:49]
	v_mfma_f32_16x16x32_bf16 v[42:45], v[160:163], v[194:197], v[42:45]
	v_mfma_f32_16x16x32_bf16 v[30:33], v[152:155], v[202:205], v[30:33]
	v_mfma_f32_16x16x32_bf16 v[26:29], v[160:163], v[202:205], v[26:29]
	v_mfma_f32_16x16x32_bf16 v[14:17], v[152:155], v[210:213], v[14:17]
	v_mfma_f32_16x16x32_bf16 v[10:13], v[160:163], v[210:213], v[10:13]
	s_setprio 0
	s_setprio 1
	v_mfma_f32_16x16x32_bf16 v[54:57], v[164:167], v[182:185], v[54:57]
	v_mfma_f32_16x16x32_bf16 v[50:53], v[172:175], v[182:185], v[50:53]
	v_mfma_f32_16x16x32_bf16 v[38:41], v[164:167], v[190:193], v[38:41]
	v_mfma_f32_16x16x32_bf16 v[34:37], v[172:175], v[190:193], v[34:37]
	v_mfma_f32_16x16x32_bf16 v[22:25], v[164:167], v[198:201], v[22:25]
	v_mfma_f32_16x16x32_bf16 v[18:21], v[172:175], v[198:201], v[18:21]
	v_mfma_f32_16x16x32_bf16 v[6:9], v[164:167], v[206:209], v[6:9]
	v_mfma_f32_16x16x32_bf16 v[2:5], v[172:175], v[206:209], v[2:5]
	v_mfma_f32_16x16x32_bf16 v[54:57], v[168:171], v[186:189], v[54:57]
	v_mfma_f32_16x16x32_bf16 v[50:53], v[176:179], v[186:189], v[50:53]
	v_mfma_f32_16x16x32_bf16 v[38:41], v[168:171], v[194:197], v[38:41]
	v_mfma_f32_16x16x32_bf16 v[34:37], v[176:179], v[194:197], v[34:37]
	v_mfma_f32_16x16x32_bf16 v[22:25], v[168:171], v[202:205], v[22:25]
	v_mfma_f32_16x16x32_bf16 v[18:21], v[176:179], v[202:205], v[18:21]
	v_mfma_f32_16x16x32_bf16 v[6:9], v[168:171], v[210:213], v[6:9]
	v_mfma_f32_16x16x32_bf16 v[2:5], v[176:179], v[210:213], v[2:5]
	s_setprio 0
	s_add_i32 s50, s50, 2
	s_add_u32 s20, s20, 0x100
	s_addc_u32 s21, s21, 0
	s_add_u32 s48, s48, 0x100
	s_addc_u32 s49, s49, 0
	s_add_u32 s22, s20, 0xfffc0080
	s_addc_u32 s23, s21, -1
	s_add_i32 s51, 0, 0x10000
	s_cmp_eq_u32 s50, 12
	s_cselect_b32 s25, s15, s23
	s_cselect_b32 s24, s46, s22
	s_cselect_b32 s23, s13, s49
	s_cselect_b32 s22, s47, s48
	s_add_i32 s54, 0, 0x14000
	s_cmp_gt_u32 s50, 13
	s_barrier
	s_cbranch_scc0 .Lrot_1550
	s_and_b64 vcc, exec, s[10:11]
	s_cbranch_vccz .LBB0_1553
	s_barrier

; #define PG8_STAGE(bufoff, gbase, voff) do { _Pragma("unroll") for (int _i = 0; _i < 2; ++_i) \
;         __builtin_amdgcn_global_load_lds((const unsigned*)((const char*)(gbase) + (voff)[_i]), (LAS unsigned*)(lds + (bufoff) + ldsw + _i * 8192), 16, 0, 0); } while (0)
; #define PG8_LDA(dst, b, h) do { _Pragma("unroll") for (int m = 0; m < 4; ++m) _Pragma("unroll") for (int k = 0; k < 2; ++k) dst[m][k] = *(const LAS bf16x8*)(lds + PG8_SA(b, h) + aoff + m * 2048 + k * 1024); } while (0)
; #define PG8_LDB(dst, b, h) do { _Pragma("unroll") for (int n = 0; n < 2; ++n) _Pragma("unroll") for (int k = 0; k < 2; ++k) dst[n][k] = *(const LAS bf16x8*)(lds + PG8_SB(b, h) + boff + n * 2048 + k * 1024); } while (0)
; #define PG8_MMA(ai, bj, At, Bt) do { __builtin_amdgcn_s_setprio(1); _Pragma("unroll") for (int m = 0; m < 4; ++m) _Pragma("unroll") for (int n = 0; n < 2; ++n) _Pragma("unroll") for (int k = 0; k < 2; ++k) \
;         acc[ai][bj][m][n] = __builtin_amdgcn_mfma_f32_16x16x32_bf16(Bt[n][k], At[m][k], acc[ai][bj][m][n], 0, 0, 0); __builtin_amdgcn_s_setprio(0); } while (0)
; #define PG8_WAIT_V(n) asm volatile("s_waitcnt vmcnt(" #n ")" ::: "memory")
; #define PG8_WAIT_L(n) asm volatile("s_waitcnt lgkmcnt(" #n ")" ::: "memory")
; #define PG8_BAR __builtin_amdgcn_s_barrier()
; #define PG8_SCHED __builtin_amdgcn_sched_barrier(0)
; template <class Epi>
; __device__ __forceinline__ void gemm_phase(LAS unsigned char* lds, const Gemm g, const StaticOrder& S, const Epi& E) {
;     ...
;             PG8_LDB(B0, 0, 0); PG8_LDB(B1, 0, 1); PG8_SCHED; PG8_LDA(At, 0, 0); PG8_STAGE(PG8_SA(1, 1), a1 + hA, voffA);
;             PG8_WAIT_V(8); PG8_WAIT_L(0); PG8_BAR; PG8_MMA(0, 0, At, B0); PG8_MMA(0, 1, At, B1); PG8_BAR; PG8_SCHED;
;             PG8_LDA(At, 0, 1); PG8_STAGE(PG8_SB(0, 0), b2, voffB); PG8_STAGE(PG8_SB(0, 1), b2 + hB, voffB); PG8_STAGE(PG8_SA(0, 0), a2, voffA);
;             PG8_WAIT_V(8); PG8_WAIT_L(0); PG8_BAR; PG8_MMA(1, 0, At, B0); PG8_MMA(1, 1, At, B1); PG8_BAR; PG8_SCHED;
.Lrot_1632:
	s_waitcnt lgkmcnt(0)
	v_add_u32_e32 v158, s70, v180
	v_add_u32_e32 v174, s71, v180
	ds_read_b128 v[146:149], v158
	ds_read_b128 v[150:153], v158 offset:1024
	ds_read_b128 v[154:157], v158 offset:2048
	ds_read_b128 v[158:161], v158 offset:3072
	ds_read_b128 v[162:165], v174
	ds_read_b128 v[166:169], v174 offset:1024
	ds_read_b128 v[170:173], v174 offset:2048
	ds_read_b128 v[174:177], v174 offset:3072
	v_lshl_add_u64 v[178:179], s[10:11], 0, v[142:143]
	s_add_i32 m0, s52, 0xc000
	ds_read_b128 v[182:185], v192
	ds_read_b128 v[196:199], v192 offset:1024
	ds_read_b128 v[200:203], v192 offset:2048
	ds_read_b128 v[204:207], v192 offset:3072
	ds_read_b128 v[208:211], v192 offset:4096
	ds_read_b128 v[212:215], v192 offset:5120
	ds_read_b128 v[216:219], v192 offset:6144
	ds_read_b128 v[232:235], v192 offset:7168
	global_load_lds_dwordx4 v[178:179], off
	v_lshl_add_u64 v[178:179], s[10:11], 0, v[144:145]
	s_add_i32 m0, s52, 0xe000
	s_nop 0
	global_load_lds_dwordx4 v[178:179], off
	s_waitcnt vmcnt(8)
	s_waitcnt lgkmcnt(0)
	s_barrier
	s_setprio 1
	s_waitcnt lgkmcnt(0)
	v_mfma_f32_16x16x32_bf16 v[26:29], v[146:149], v[182:185], v[26:29]
	v_mfma_f32_16x16x32_bf16 v[30:33], v[154:157], v[182:185], v[30:33]
	v_mfma_f32_16x16x32_bf16 v[58:61], v[146:149], v[200:203], v[58:61]
	v_mfma_f32_16x16x32_bf16 v[62:65], v[154:157], v[200:203], v[62:65]
	v_mfma_f32_16x16x32_bf16 v[90:93], v[146:149], v[208:211], v[90:93]
	v_mfma_f32_16x16x32_bf16 v[94:97], v[154:157], v[208:211], v[94:97]
	v_mfma_f32_16x16x32_bf16 v[114:117], v[146:149], v[216:219], v[114:117]
	v_mfma_f32_16x16x32_bf16 v[118:121], v[154:157], v[216:219], v[118:121]
	v_mfma_f32_16x16x32_bf16 v[26:29], v[150:153], v[196:199], v[26:29]
	v_mfma_f32_16x16x32_bf16 v[30:33], v[158:161], v[196:199], v[30:33]
	v_mfma_f32_16x16x32_bf16 v[58:61], v[150:153], v[204:207], v[58:61]
	v_mfma_f32_16x16x32_bf16 v[62:65], v[158:161], v[204:207], v[62:65]
	v_mfma_f32_16x16x32_bf16 v[90:93], v[150:153], v[212:215], v[90:93]
	v_mfma_f32_16x16x32_bf16 v[94:97], v[158:161], v[212:215], v[94:97]
	v_mfma_f32_16x16x32_bf16 v[114:117], v[150:153], v[232:235], v[114:117]
	v_mfma_f32_16x16x32_bf16 v[118:121], v[158:161], v[232:235], v[118:121]
	s_setprio 0
	s_setprio 1
	v_mfma_f32_16x16x32_bf16 v[42:45], v[162:165], v[182:185], v[42:45]
	v_mfma_f32_16x16x32_bf16 v[46:49], v[170:173], v[182:185], v[46:49]
	v_mfma_f32_16x16x32_bf16 v[74:77], v[162:165], v[200:203], v[74:77]
	v_mfma_f32_16x16x32_bf16 v[78:81], v[170:173], v[200:203], v[78:81]
	v_mfma_f32_16x16x32_bf16 v[106:109], v[162:165], v[208:211], v[106:109]
	v_mfma_f32_16x16x32_bf16 v[110:113], v[170:173], v[208:211], v[110:113]
	v_mfma_f32_16x16x32_bf16 v[126:129], v[162:165], v[216:219], v[126:129]
	v_mfma_f32_16x16x32_bf16 v[122:125], v[170:173], v[216:219], v[122:125]
	v_mfma_f32_16x16x32_bf16 v[42:45], v[166:169], v[196:199], v[42:45]
	v_mfma_f32_16x16x32_bf16 v[46:49], v[174:177], v[196:199], v[46:49]
	v_mfma_f32_16x16x32_bf16 v[74:77], v[166:169], v[204:207], v[74:77]
	v_mfma_f32_16x16x32_bf16 v[78:81], v[174:177], v[204:207], v[78:81]
	v_mfma_f32_16x16x32_bf16 v[106:109], v[166:169], v[212:215], v[106:109]
	v_mfma_f32_16x16x32_bf16 v[110:113], v[174:177], v[212:215], v[110:113]
	v_mfma_f32_16x16x32_bf16 v[126:129], v[166:169], v[232:235], v[126:129]
	v_mfma_f32_16x16x32_bf16 v[122:125], v[174:177], v[232:235], v[122:125]
	s_setprio 0
	s_barrier
	s_add_i32 s10, s70, s47
	v_lshl_add_u64 v[178:179], s[42:43], 0, v[132:133]
	s_mov_b32 m0, s10
	ds_read_b128 v[182:185], v192 offset:16384
	ds_read_b128 v[196:199], v192 offset:17408
	ds_read_b128 v[200:203], v192 offset:18432
	ds_read_b128 v[204:207], v192 offset:19456
	ds_read_b128 v[208:211], v192 offset:20480
	ds_read_b128 v[212:215], v192 offset:21504
	ds_read_b128 v[216:219], v192 offset:22528
	ds_read_b128 v[232:235], v192 offset:23552
	global_load_lds_dwordx4 v[178:179], off
	s_add_i32 m0, s10, 0x2000
	s_add_u32 s10, s42, 0xb0000
	v_lshl_add_u64 v[186:187], s[42:43], 0, v[136:137]
	s_addc_u32 s11, s43, 0
	s_add_i32 s70, s71, s47
	global_load_lds_dwordx4 v[186:187], off
	v_lshl_add_u64 v[220:221], s[10:11], 0, v[132:133]
	s_mov_b32 m0, s70
	v_lshl_add_u64 v[236:237], s[44:45], 0, v[134:135]
	global_load_lds_dwordx4 v[220:221], off
	v_lshl_add_u64 v[220:221], s[10:11], 0, v[136:137]
	s_add_i32 m0, s70, 0x2000
	s_nop 0
	global_load_lds_dwordx4 v[220:221], off
	v_lshl_add_u64 v[220:221], s[44:45], 0, v[130:131]
	s_mov_b32 m0, s52
	s_nop 0
	global_load_lds_dwordx4 v[220:221], off
	s_mov_b32 m0, s53
	s_nop 0
	global_load_lds_dwordx4 v[236:237], off
	s_waitcnt vmcnt(8)
	s_waitcnt lgkmcnt(0)
	s_barrier
; #define PG8_STAGE(bufoff, gbase, voff) do { _Pragma("unroll") for (int _i = 0; _i < 2; ++_i) \
;         __builtin_amdgcn_global_load_lds((const unsigned*)((const char*)(gbase) + (voff)[_i]), (LAS unsigned*)(lds + (bufoff) + ldsw + _i * 8192), 16, 0, 0); } while (0)
; #define PG8_LDA(dst, b, h) do { _Pragma("unroll") for (int m = 0; m < 4; ++m) _Pragma("unroll") for (int k = 0; k < 2; ++k) dst[m][k] = *(const LAS bf16x8*)(lds + PG8_SA(b, h) + aoff + m * 2048 + k * 1024); } while (0)
; #define PG8_LDB(dst, b, h) do { _Pragma("unroll") for (int n = 0; n < 2; ++n) _Pragma("unroll") for (int k = 0; k < 2; ++k) dst[n][k] = *(const LAS bf16x8*)(lds + PG8_SB(b, h) + boff + n * 2048 + k * 1024); } while (0)
; #define PG8_MMA(ai, bj, At, Bt) do { __builtin_amdgcn_s_setprio(1); _Pragma("unroll") for (int m = 0; m < 4; ++m) _Pragma("unroll") for (int n = 0; n < 2; ++n) _Pragma("unroll") for (int k = 0; k < 2; ++k) \
;         acc[ai][bj][m][n] = __builtin_amdgcn_mfma_f32_16x16x32_bf16(Bt[n][k], At[m][k], acc[ai][bj][m][n], 0, 0, 0); __builtin_amdgcn_s_setprio(0); } while (0)
; #define PG8_WAIT_V(n) asm volatile("s_waitcnt vmcnt(" #n ")" ::: "memory")
; #define PG8_WAIT_L(n) asm volatile("s_waitcnt lgkmcnt(" #n ")" ::: "memory")
; #define PG8_BAR __builtin_amdgcn_s_barrier()
; #define PG8_SCHED __builtin_amdgcn_sched_barrier(0)
; template <class Epi>
; __device__ __forceinline__ void gemm_phase(LAS unsigned char* lds, const Gemm g, const StaticOrder& S, const Epi& E) {
;     ...
;             PG8_WAIT_V(8); PG8_WAIT_L(0); PG8_BAR; PG8_MMA(1, 0, At, B0); PG8_MMA(1, 1, At, B1); PG8_BAR; PG8_SCHED;
;             PG8_LDB(B0, 1, 0); PG8_LDB(B1, 1, 1); PG8_SCHED; PG8_LDA(At, 1, 0); PG8_STAGE(PG8_SA(0, 1), a2 + hA, voffA);
;             PG8_WAIT_V(8); PG8_WAIT_L(0); PG8_BAR; PG8_MMA(0, 0, At, B0); PG8_MMA(0, 1, At, B1); PG8_BAR; PG8_SCHED;
	s_setprio 1
	s_waitcnt lgkmcnt(0)
	v_mfma_f32_16x16x32_bf16 v[102:105], v[146:149], v[182:185], v[102:105]
	v_mfma_f32_16x16x32_bf16 v[98:101], v[154:157], v[182:185], v[98:101]
	v_mfma_f32_16x16x32_bf16 v[70:73], v[146:149], v[200:203], v[70:73]
	v_mfma_f32_16x16x32_bf16 v[66:69], v[154:157], v[200:203], v[66:69]
	v_mfma_f32_16x16x32_bf16 v[38:41], v[146:149], v[208:211], v[38:41]
	v_mfma_f32_16x16x32_bf16 v[34:37], v[154:157], v[208:211], v[34:37]
	v_mfma_f32_16x16x32_bf16 v[14:17], v[146:149], v[216:219], v[14:17]
	v_mfma_f32_16x16x32_bf16 v[10:13], v[154:157], v[216:219], v[10:13]
	v_mfma_f32_16x16x32_bf16 v[102:105], v[150:153], v[196:199], v[102:105]
	v_mfma_f32_16x16x32_bf16 v[98:101], v[158:161], v[196:199], v[98:101]
	v_mfma_f32_16x16x32_bf16 v[70:73], v[150:153], v[204:207], v[70:73]
	v_mfma_f32_16x16x32_bf16 v[66:69], v[158:161], v[204:207], v[66:69]
	v_mfma_f32_16x16x32_bf16 v[38:41], v[150:153], v[212:215], v[38:41]
	v_mfma_f32_16x16x32_bf16 v[34:37], v[158:161], v[212:215], v[34:37]
	v_mfma_f32_16x16x32_bf16 v[14:17], v[150:153], v[232:235], v[14:17]
	v_mfma_f32_16x16x32_bf16 v[10:13], v[158:161], v[232:235], v[10:13]
	s_setprio 0
	s_setprio 1
	v_mfma_f32_16x16x32_bf16 v[86:89], v[162:165], v[182:185], v[86:89]
	v_mfma_f32_16x16x32_bf16 v[82:85], v[170:173], v[182:185], v[82:85]
	v_mfma_f32_16x16x32_bf16 v[54:57], v[162:165], v[200:203], v[54:57]
	v_mfma_f32_16x16x32_bf16 v[50:53], v[170:173], v[200:203], v[50:53]
	v_mfma_f32_16x16x32_bf16 v[22:25], v[162:165], v[208:211], v[22:25]
	v_mfma_f32_16x16x32_bf16 v[18:21], v[170:173], v[208:211], v[18:21]
	v_mfma_f32_16x16x32_bf16 v[6:9], v[162:165], v[216:219], v[6:9]
	v_mfma_f32_16x16x32_bf16 v[2:5], v[170:173], v[216:219], v[2:5]
	v_mfma_f32_16x16x32_bf16 v[86:89], v[166:169], v[196:199], v[86:89]
	v_mfma_f32_16x16x32_bf16 v[82:85], v[174:177], v[196:199], v[82:85]
	v_mfma_f32_16x16x32_bf16 v[54:57], v[166:169], v[204:207], v[54:57]
	v_mfma_f32_16x16x32_bf16 v[50:53], v[174:177], v[204:207], v[50:53]
	v_mfma_f32_16x16x32_bf16 v[22:25], v[166:169], v[212:215], v[22:25]
	v_mfma_f32_16x16x32_bf16 v[18:21], v[174:177], v[212:215], v[18:21]
	v_mfma_f32_16x16x32_bf16 v[6:9], v[166:169], v[232:235], v[6:9]
	v_mfma_f32_16x16x32_bf16 v[2:5], v[174:177], v[232:235], v[2:5]
	s_setprio 0
	s_barrier
	s_add_i32 s70, 0, 0x18000
	s_add_i32 s71, 0, 0x1c000
	v_add_u32_e32 v158, s70, v180
	v_add_u32_e32 v174, s71, v180
	ds_read_b128 v[146:149], v158
	ds_read_b128 v[150:153], v158 offset:1024
	ds_read_b128 v[154:157], v158 offset:2048
	ds_read_b128 v[158:161], v158 offset:3072
	ds_read_b128 v[162:165], v174
	ds_read_b128 v[166:169], v174 offset:1024
	ds_read_b128 v[170:173], v174 offset:2048
	ds_read_b128 v[174:177], v174 offset:3072
	s_add_u32 s10, s44, 0xb0000
	s_addc_u32 s11, s45, 0
	s_mov_b32 m0, s54
	v_lshl_add_u64 v[238:239], s[10:11], 0, v[130:131]
	ds_read_b128 v[182:185], v192 offset:32768
	ds_read_b128 v[196:199], v192 offset:33792
	ds_read_b128 v[200:203], v192 offset:34816
	ds_read_b128 v[204:207], v192 offset:35840
	ds_read_b128 v[208:211], v192 offset:36864
	ds_read_b128 v[212:215], v192 offset:37888
	ds_read_b128 v[216:219], v192 offset:38912
	ds_read_b128 v[232:235], v192 offset:39936
	global_load_lds_dwordx4 v[238:239], off
	v_lshl_add_u64 v[238:239], s[10:11], 0, v[134:135]
	s_mov_b32 m0, s55
	s_nop 0
	global_load_lds_dwordx4 v[238:239], off
	s_waitcnt vmcnt(8)
	s_waitcnt lgkmcnt(0)
	s_barrier
	s_setprio 1
	s_waitcnt lgkmcnt(0)
	v_mfma_f32_16x16x32_bf16 v[26:29], v[146:149], v[182:185], v[26:29]
	v_mfma_f32_16x16x32_bf16 v[30:33], v[154:157], v[182:185], v[30:33]
	v_mfma_f32_16x16x32_bf16 v[58:61], v[146:149], v[200:203], v[58:61]
	v_mfma_f32_16x16x32_bf16 v[62:65], v[154:157], v[200:203], v[62:65]
	v_mfma_f32_16x16x32_bf16 v[90:93], v[146:149], v[208:211], v[90:93]
	v_mfma_f32_16x16x32_bf16 v[94:97], v[154:157], v[208:211], v[94:97]
	v_mfma_f32_16x16x32_bf16 v[114:117], v[146:149], v[216:219], v[114:117]
	v_mfma_f32_16x16x32_bf16 v[118:121], v[154:157], v[216:219], v[118:121]
	v_mfma_f32_16x16x32_bf16 v[26:29], v[150:153], v[196:199], v[26:29]
	v_mfma_f32_16x16x32_bf16 v[30:33], v[158:161], v[196:199], v[30:33]
	v_mfma_f32_16x16x32_bf16 v[58:61], v[150:153], v[204:207], v[58:61]
	v_mfma_f32_16x16x32_bf16 v[62:65], v[158:161], v[204:207], v[62:65]
	v_mfma_f32_16x16x32_bf16 v[90:93], v[150:153], v[212:215], v[90:93]
	v_mfma_f32_16x16x32_bf16 v[94:97], v[158:161], v[212:215], v[94:97]
	v_mfma_f32_16x16x32_bf16 v[114:117], v[150:153], v[232:235], v[114:117]
	v_mfma_f32_16x16x32_bf16 v[118:121], v[158:161], v[232:235], v[118:121]
	s_setprio 0
	s_setprio 1
	v_mfma_f32_16x16x32_bf16 v[42:45], v[162:165], v[182:185], v[42:45]
	v_mfma_f32_16x16x32_bf16 v[46:49], v[170:173], v[182:185], v[46:49]
	v_mfma_f32_16x16x32_bf16 v[74:77], v[162:165], v[200:203], v[74:77]
	v_mfma_f32_16x16x32_bf16 v[78:81], v[170:173], v[200:203], v[78:81]
	v_mfma_f32_16x16x32_bf16 v[106:109], v[162:165], v[208:211], v[106:109]
	v_mfma_f32_16x16x32_bf16 v[110:113], v[170:173], v[208:211], v[110:113]
	v_mfma_f32_16x16x32_bf16 v[126:129], v[162:165], v[216:219], v[126:129]
	v_mfma_f32_16x16x32_bf16 v[122:125], v[170:173], v[216:219], v[122:125]
	v_mfma_f32_16x16x32_bf16 v[42:45], v[166:169], v[196:199], v[42:45]
	v_mfma_f32_16x16x32_bf16 v[46:49], v[174:177], v[196:199], v[46:49]
	v_mfma_f32_16x16x32_bf16 v[74:77], v[166:169], v[204:207], v[74:77]
	v_mfma_f32_16x16x32_bf16 v[78:81], v[174:177], v[204:207], v[78:81]
	v_mfma_f32_16x16x32_bf16 v[106:109], v[166:169], v[212:215], v[106:109]
	v_mfma_f32_16x16x32_bf16 v[110:113], v[174:177], v[212:215], v[110:113]
	v_mfma_f32_16x16x32_bf16 v[126:129], v[166:169], v[232:235], v[126:129]
	v_mfma_f32_16x16x32_bf16 v[122:125], v[174:177], v[232:235], v[122:125]
	s_setprio 0
	s_barrier
; #define PG8_STAGE(bufoff, gbase, voff) do { _Pragma("unroll") for (int _i = 0; _i < 2; ++_i) \
;         __builtin_amdgcn_global_load_lds((const unsigned*)((const char*)(gbase) + (voff)[_i]), (LAS unsigned*)(lds + (bufoff) + ldsw + _i * 8192), 16, 0, 0); } while (0)
; #define PG8_LDA(dst, b, h) do { _Pragma("unroll") for (int m = 0; m < 4; ++m) _Pragma("unroll") for (int k = 0; k < 2; ++k) dst[m][k] = *(const LAS bf16x8*)(lds + PG8_SA(b, h) + aoff + m * 2048 + k * 1024); } while (0)
; #define PG8_MMA(ai, bj, At, Bt) do { __builtin_amdgcn_s_setprio(1); _Pragma("unroll") for (int m = 0; m < 4; ++m) _Pragma("unroll") for (int n = 0; n < 2; ++n) _Pragma("unroll") for (int k = 0; k < 2; ++k) \
;         acc[ai][bj][m][n] = __builtin_amdgcn_mfma_f32_16x16x32_bf16(Bt[n][k], At[m][k], acc[ai][bj][m][n], 0, 0, 0); __builtin_amdgcn_s_setprio(0); } while (0)
; #define PG8_WAIT_V(n) asm volatile("s_waitcnt vmcnt(" #n ")" ::: "memory")
; #define PG8_WAIT_L(n) asm volatile("s_waitcnt lgkmcnt(" #n ")" ::: "memory")
; #define PG8_BAR __builtin_amdgcn_s_barrier()
; #define PG8_SCHED __builtin_amdgcn_sched_barrier(0)
; template <class Epi>
; __device__ __forceinline__ void gemm_phase(LAS unsigned char* lds, const Gemm g, const StaticOrder& S, const Epi& E) {
;     ...
;         for (int t = 0; t < nt; t += 2) {
;             const bool last = (t == nt - 2);
;             const char* a1 = cA + (size_t)(t + 1) * kstep;
;             const char* a2 = last ? nA : cA + (size_t)(t + 2) * kstep; const char* b2 = last ? nB : cB + (size_t)(t + 2) * kstep;
;             const char* a3 = a2 + kstep; const char* b3 = b2 + kstep;
;     ...
;             PG8_LDA(At, 1, 1); PG8_STAGE(PG8_SB(1, 0), b3, voffB); PG8_STAGE(PG8_SB(1, 1), b3 + hB, voffB); PG8_STAGE(PG8_SA(1, 0), a3, voffA);
;             PG8_WAIT_V(8); PG8_WAIT_L(0); PG8_BAR; PG8_MMA(1, 0, At, B0); PG8_MMA(1, 1, At, B1); PG8_BAR; PG8_SCHED;
	s_add_i32 s10, s70, s47
	v_lshl_add_u64 v[178:179], v[178:179], 0, s[88:89]
	s_mov_b32 m0, s10
	ds_read_b128 v[182:185], v192 offset:49152
	ds_read_b128 v[196:199], v192 offset:50176
	ds_read_b128 v[200:203], v192 offset:51200
	ds_read_b128 v[204:207], v192 offset:52224
	ds_read_b128 v[208:211], v192 offset:53248
	ds_read_b128 v[212:215], v192 offset:54272
	ds_read_b128 v[216:219], v192 offset:55296
	ds_read_b128 v[232:235], v192 offset:56320
	global_load_lds_dwordx4 v[178:179], off
	s_add_i32 m0, s10, 0x2000
	s_add_u32 s10, s42, 0xb0080
	v_lshl_add_u64 v[178:179], v[186:187], 0, s[88:89]
	s_addc_u32 s11, s43, 0
	s_add_i32 s42, s71, s47
	global_load_lds_dwordx4 v[178:179], off
	v_lshl_add_u64 v[178:179], s[10:11], 0, v[132:133]
	s_mov_b32 m0, s42
	s_nop 0
	global_load_lds_dwordx4 v[178:179], off
	v_lshl_add_u64 v[178:179], s[10:11], 0, v[136:137]
	s_add_i32 m0, s42, 0x2000
	s_nop 0
	global_load_lds_dwordx4 v[178:179], off
	v_lshl_add_u64 v[178:179], v[220:221], 0, s[88:89]
	s_mov_b32 m0, s56
	s_nop 0
	global_load_lds_dwordx4 v[178:179], off
	v_lshl_add_u64 v[178:179], v[236:237], 0, s[88:89]
	s_mov_b32 m0, s57
	s_nop 0
	global_load_lds_dwordx4 v[178:179], off
	s_waitcnt vmcnt(8)
	s_waitcnt lgkmcnt(0)
	s_barrier
	s_setprio 1
	s_waitcnt lgkmcnt(0)
	v_mfma_f32_16x16x32_bf16 v[102:105], v[146:149], v[182:185], v[102:105]
	v_mfma_f32_16x16x32_bf16 v[98:101], v[154:157], v[182:185], v[98:101]
	v_mfma_f32_16x16x32_bf16 v[70:73], v[146:149], v[200:203], v[70:73]
	v_mfma_f32_16x16x32_bf16 v[66:69], v[154:157], v[200:203], v[66:69]
	v_mfma_f32_16x16x32_bf16 v[38:41], v[146:149], v[208:211], v[38:41]
	v_mfma_f32_16x16x32_bf16 v[34:37], v[154:157], v[208:211], v[34:37]
	v_mfma_f32_16x16x32_bf16 v[14:17], v[146:149], v[216:219], v[14:17]
	v_mfma_f32_16x16x32_bf16 v[10:13], v[154:157], v[216:219], v[10:13]
	v_mfma_f32_16x16x32_bf16 v[102:105], v[150:153], v[196:199], v[102:105]
	v_mfma_f32_16x16x32_bf16 v[98:101], v[158:161], v[196:199], v[98:101]
	v_mfma_f32_16x16x32_bf16 v[70:73], v[150:153], v[204:207], v[70:73]
	v_mfma_f32_16x16x32_bf16 v[66:69], v[158:161], v[204:207], v[66:69]
	v_mfma_f32_16x16x32_bf16 v[38:41], v[150:153], v[212:215], v[38:41]
	v_mfma_f32_16x16x32_bf16 v[34:37], v[158:161], v[212:215], v[34:37]
	v_mfma_f32_16x16x32_bf16 v[14:17], v[150:153], v[232:235], v[14:17]
	v_mfma_f32_16x16x32_bf16 v[10:13], v[158:161], v[232:235], v[10:13]
	s_setprio 0
	s_setprio 1
	v_mfma_f32_16x16x32_bf16 v[86:89], v[162:165], v[182:185], v[86:89]
	v_mfma_f32_16x16x32_bf16 v[82:85], v[170:173], v[182:185], v[82:85]
	v_mfma_f32_16x16x32_bf16 v[54:57], v[162:165], v[200:203], v[54:57]
	v_mfma_f32_16x16x32_bf16 v[50:53], v[170:173], v[200:203], v[50:53]
	v_mfma_f32_16x16x32_bf16 v[22:25], v[162:165], v[208:211], v[22:25]
	v_mfma_f32_16x16x32_bf16 v[18:21], v[170:173], v[208:211], v[18:21]
	v_mfma_f32_16x16x32_bf16 v[6:9], v[162:165], v[216:219], v[6:9]
	v_mfma_f32_16x16x32_bf16 v[2:5], v[170:173], v[216:219], v[2:5]
	v_mfma_f32_16x16x32_bf16 v[86:89], v[166:169], v[196:199], v[86:89]
	v_mfma_f32_16x16x32_bf16 v[82:85], v[174:177], v[196:199], v[82:85]
	v_mfma_f32_16x16x32_bf16 v[54:57], v[166:169], v[204:207], v[54:57]
	v_mfma_f32_16x16x32_bf16 v[50:53], v[174:177], v[204:207], v[50:53]
	v_mfma_f32_16x16x32_bf16 v[22:25], v[166:169], v[212:215], v[22:25]
	v_mfma_f32_16x16x32_bf16 v[18:21], v[174:177], v[212:215], v[18:21]
	v_mfma_f32_16x16x32_bf16 v[6:9], v[166:169], v[232:235], v[6:9]
	v_mfma_f32_16x16x32_bf16 v[2:5], v[174:177], v[232:235], v[2:5]
	s_setprio 0
	s_add_i32 s67, s67, 2
	s_add_u32 s35, s35, 0x100
	s_addc_u32 s37, s37, 0
	s_mov_b64 s[10:11], s[8:9]
	s_add_u32 s8, s10, 0x100
	s_addc_u32 s9, s11, 0
	s_add_i32 s70, 0, 0x10000
	s_cmp_eq_u32 s67, 40
	s_cselect_b32 s45, s39, s9
	s_cselect_b32 s44, s38, s8
	s_cselect_b32 s43, s41, s37
	s_cselect_b32 s42, s40, s35
	s_add_i32 s71, 0, 0x14000
	s_cmp_gt_u32 s67, 41
	s_barrier
	s_cbranch_scc0 .Lrot_1632
	s_and_b64 vcc, exec, s[20:21]
	s_cbranch_vccz .LBB0_1635
	s_barrier
